# residual epilogues: touch the residual rows of rounds 2-7 up front so the per-round loads hit cache
# baseline (speedup 1.0000x reference)
; #define PG8_STAGE(bufoff, gbase, voff) do { _Pragma("unroll") for (int _i = 0; _i < 2; ++_i) \
;     __builtin_amdgcn_global_load_lds((const unsigned*)((const char*)(gbase) + (voff)[_i]), (PG8_LAS unsigned*)(lds + (bufoff) + ldsw + _i * 8192), 16, 0, 0); } while (0)
; #define PG8_LDA(dst, b, h) do { _Pragma("unroll") for (int m = 0; m < 4; ++m) _Pragma("unroll") for (int k = 0; k < 2; ++k) dst[m][k] = *(const PG8_LAS bf16x8*)(lds + PG8_SA(b, h) + aoff + m * 2048 + k * 1024); } while (0)
; #define PG8_LDB(dst, b, h) do { _Pragma("unroll") for (int n = 0; n < 2; ++n) _Pragma("unroll") for (int k = 0; k < 2; ++k) dst[n][k] = *(const PG8_LAS bf16x8*)(lds + PG8_SB(b, h) + boff + n * 2048 + k * 1024); } while (0)
; #define PG8_MMA(ai, bj, At, Bt) do { __builtin_amdgcn_s_setprio(1); _Pragma("unroll") for (int m = 0; m < 4; ++m) _Pragma("unroll") for (int n = 0; n < 2; ++n) _Pragma("unroll") for (int k = 0; k < 2; ++k) \
;     acc[ai][bj][m][n] = __builtin_amdgcn_mfma_f32_16x16x32_bf16(Bt[n][k], At[m][k], acc[ai][bj][m][n], 0, 0, 0); __builtin_amdgcn_s_setprio(0); } while (0)
; #define PG8_WAIT_V(n) asm volatile("s_waitcnt vmcnt(" #n ")" ::: "memory")
; #define PG8_WAIT_L(n) asm volatile("s_waitcnt lgkmcnt(" #n ")" ::: "memory")
; #define PG8_BAR __builtin_amdgcn_s_barrier()
; #define PG8_SCHED __builtin_amdgcn_sched_barrier(0)
; template <class Epi, class Sched>
; DI void gemm_phase(PG8_LAS unsigned char* lds, const Gemm g, const Sched& S, const Epi& E) {
;     ...
;       PG8_LDB(B0, 0, 0); PG8_LDB(B1, 0, 1); PG8_SCHED; PG8_LDA(At, 0, 0); PG8_STAGE(PG8_SA(1, 1), a1 + hstepA, voffA);
;       PG8_WAIT_V(8); PG8_WAIT_L(0); PG8_BAR; PG8_MMA(0, 0, At, B0); PG8_MMA(0, 1, At, B1); PG8_BAR; PG8_SCHED;
;       PG8_LDA(At, 0, 1); PG8_STAGE(PG8_SB(0, 0), b2, voffB); PG8_STAGE(PG8_SB(0, 1), b2 + hstepB, voffB); PG8_STAGE(PG8_SA(0, 0), a2, voffA);
;       PG8_WAIT_V(8); PG8_WAIT_L(0); PG8_BAR; PG8_MMA(1, 0, At, B0); PG8_MMA(1, 1, At, B1); PG8_BAR; PG8_SCHED;
.LBB0_563:
	ds_read_b128 v[128:131], v167
	ds_read_b128 v[132:135], v167 offset:1024
	ds_read_b128 v[136:139], v167 offset:2048
	ds_read_b128 v[140:143], v167 offset:3072
	ds_read_b128 v[158:161], v168
	ds_read_b128 v[162:165], v168 offset:1024
	ds_read_b128 v[172:175], v168 offset:2048
	ds_read_b128 v[176:179], v168 offset:3072
	s_add_u32 s16, s28, 0xfffc0080
	s_addc_u32 s17, s29, -1
	s_cmp_eq_u32 s70, 12
	s_cselect_b32 s35, s19, s17
	s_cselect_b32 s34, s27, s16
	s_cselect_b32 s31, s15, s69
	s_cselect_b32 s30, s67, s68
	v_lshl_add_u64 v[214:215], s[28:29], 0, v[154:155]
	s_add_i32 m0, s3, 0xc000
	ds_read_b128 v[180:183], v169
	ds_read_b128 v[184:187], v169 offset:1024
	ds_read_b128 v[188:191], v169 offset:2048
	ds_read_b128 v[192:195], v169 offset:3072
	ds_read_b128 v[196:199], v169 offset:4096
	ds_read_b128 v[200:203], v169 offset:5120
	ds_read_b128 v[204:207], v169 offset:6144
	ds_read_b128 v[208:211], v169 offset:7168
	global_load_lds_dwordx4 v[214:215], off
	v_lshl_add_u64 v[214:215], s[28:29], 0, v[156:157]
	s_add_i32 m0, s3, 0xe000
	s_nop 0
	global_load_lds_dwordx4 v[214:215], off
	s_waitcnt vmcnt(8)
	s_waitcnt lgkmcnt(0)
	s_barrier
	s_setprio 1
	s_waitcnt lgkmcnt(0)
	v_mfma_f32_16x16x32_bf16 v[124:127], v[128:131], v[180:183], v[124:127]
	v_mfma_f32_16x16x32_bf16 v[120:123], v[136:139], v[180:183], v[120:123]
	v_mfma_f32_16x16x32_bf16 v[108:111], v[128:131], v[188:191], v[108:111]
	v_mfma_f32_16x16x32_bf16 v[104:107], v[136:139], v[188:191], v[104:107]
	v_mfma_f32_16x16x32_bf16 v[92:95], v[128:131], v[196:199], v[92:95]
	v_mfma_f32_16x16x32_bf16 v[88:91], v[136:139], v[196:199], v[88:91]
	v_mfma_f32_16x16x32_bf16 v[76:79], v[128:131], v[204:207], v[76:79]
	v_mfma_f32_16x16x32_bf16 v[72:75], v[136:139], v[204:207], v[72:75]
	v_mfma_f32_16x16x32_bf16 v[124:127], v[132:135], v[184:187], v[124:127]
	v_mfma_f32_16x16x32_bf16 v[120:123], v[140:143], v[184:187], v[120:123]
	v_mfma_f32_16x16x32_bf16 v[108:111], v[132:135], v[192:195], v[108:111]
	v_mfma_f32_16x16x32_bf16 v[104:107], v[140:143], v[192:195], v[104:107]
	v_mfma_f32_16x16x32_bf16 v[92:95], v[132:135], v[200:203], v[92:95]
	v_mfma_f32_16x16x32_bf16 v[88:91], v[140:143], v[200:203], v[88:91]
	v_mfma_f32_16x16x32_bf16 v[76:79], v[132:135], v[208:211], v[76:79]
	v_mfma_f32_16x16x32_bf16 v[72:75], v[140:143], v[208:211], v[72:75]
	s_setprio 0
	s_setprio 1
	v_mfma_f32_16x16x32_bf16 v[116:119], v[158:161], v[180:183], v[116:119]
	v_mfma_f32_16x16x32_bf16 v[112:115], v[172:175], v[180:183], v[112:115]
	v_mfma_f32_16x16x32_bf16 v[100:103], v[158:161], v[188:191], v[100:103]
	v_mfma_f32_16x16x32_bf16 v[96:99], v[172:175], v[188:191], v[96:99]
	v_mfma_f32_16x16x32_bf16 v[84:87], v[158:161], v[196:199], v[84:87]
	v_mfma_f32_16x16x32_bf16 v[80:83], v[172:175], v[196:199], v[80:83]
	v_mfma_f32_16x16x32_bf16 v[68:71], v[158:161], v[204:207], v[68:71]
	v_mfma_f32_16x16x32_bf16 v[64:67], v[172:175], v[204:207], v[64:67]
	v_mfma_f32_16x16x32_bf16 v[116:119], v[162:165], v[184:187], v[116:119]
	v_mfma_f32_16x16x32_bf16 v[112:115], v[176:179], v[184:187], v[112:115]
	v_mfma_f32_16x16x32_bf16 v[100:103], v[162:165], v[192:195], v[100:103]
	v_mfma_f32_16x16x32_bf16 v[96:99], v[176:179], v[192:195], v[96:99]
	v_mfma_f32_16x16x32_bf16 v[84:87], v[162:165], v[200:203], v[84:87]
	v_mfma_f32_16x16x32_bf16 v[80:83], v[176:179], v[200:203], v[80:83]
	v_mfma_f32_16x16x32_bf16 v[68:71], v[162:165], v[208:211], v[68:71]
	v_mfma_f32_16x16x32_bf16 v[64:67], v[176:179], v[208:211], v[64:67]
	s_setprio 0
	s_barrier
	s_add_i32 s16, s55, s2
	v_lshl_add_u64 v[214:215], s[30:31], 0, v[146:147]
	s_mov_b32 m0, s16
	ds_read_b128 v[180:183], v169 offset:16384
	ds_read_b128 v[184:187], v169 offset:17408
	ds_read_b128 v[188:191], v169 offset:18432
	ds_read_b128 v[192:195], v169 offset:19456
	ds_read_b128 v[196:199], v169 offset:20480
	ds_read_b128 v[200:203], v169 offset:21504
	ds_read_b128 v[204:207], v169 offset:22528
	ds_read_b128 v[208:211], v169 offset:23552
	global_load_lds_dwordx4 v[214:215], off
	s_add_i32 m0, s16, 0x2000
	s_add_u32 s16, s30, 0x40000
	v_lshl_add_u64 v[216:217], s[30:31], 0, v[150:151]
	s_addc_u32 s17, s31, 0
	s_add_i32 s33, s64, s2
	global_load_lds_dwordx4 v[216:217], off
	v_lshl_add_u64 v[218:219], s[16:17], 0, v[146:147]
	s_mov_b32 m0, s33
	v_lshl_add_u64 v[220:221], s[34:35], 0, v[148:149]
	global_load_lds_dwordx4 v[218:219], off
	v_lshl_add_u64 v[218:219], s[16:17], 0, v[150:151]
	s_add_i32 m0, s33, 0x2000
	s_nop 0
	global_load_lds_dwordx4 v[218:219], off
	v_lshl_add_u64 v[218:219], s[34:35], 0, v[144:145]
	s_mov_b32 m0, s3
	s_nop 0
	global_load_lds_dwordx4 v[218:219], off
	s_mov_b32 m0, s36
	s_nop 0
	global_load_lds_dwordx4 v[220:221], off
	s_waitcnt vmcnt(8)
	s_waitcnt lgkmcnt(0)
	s_barrier
; #define PG8_STAGE(bufoff, gbase, voff) do { _Pragma("unroll") for (int _i = 0; _i < 2; ++_i) \
;     __builtin_amdgcn_global_load_lds((const unsigned*)((const char*)(gbase) + (voff)[_i]), (PG8_LAS unsigned*)(lds + (bufoff) + ldsw + _i * 8192), 16, 0, 0); } while (0)
; #define PG8_LDA(dst, b, h) do { _Pragma("unroll") for (int m = 0; m < 4; ++m) _Pragma("unroll") for (int k = 0; k < 2; ++k) dst[m][k] = *(const PG8_LAS bf16x8*)(lds + PG8_SA(b, h) + aoff + m * 2048 + k * 1024); } while (0)
; #define PG8_LDB(dst, b, h) do { _Pragma("unroll") for (int n = 0; n < 2; ++n) _Pragma("unroll") for (int k = 0; k < 2; ++k) dst[n][k] = *(const PG8_LAS bf16x8*)(lds + PG8_SB(b, h) + boff + n * 2048 + k * 1024); } while (0)
; #define PG8_MMA(ai, bj, At, Bt) do { __builtin_amdgcn_s_setprio(1); _Pragma("unroll") for (int m = 0; m < 4; ++m) _Pragma("unroll") for (int n = 0; n < 2; ++n) _Pragma("unroll") for (int k = 0; k < 2; ++k) \
;     acc[ai][bj][m][n] = __builtin_amdgcn_mfma_f32_16x16x32_bf16(Bt[n][k], At[m][k], acc[ai][bj][m][n], 0, 0, 0); __builtin_amdgcn_s_setprio(0); } while (0)
; #define PG8_WAIT_V(n) asm volatile("s_waitcnt vmcnt(" #n ")" ::: "memory")
; #define PG8_WAIT_L(n) asm volatile("s_waitcnt lgkmcnt(" #n ")" ::: "memory")
; #define PG8_BAR __builtin_amdgcn_s_barrier()
; #define PG8_SCHED __builtin_amdgcn_sched_barrier(0)
; template <class Epi, class Sched>
; DI void gemm_phase(PG8_LAS unsigned char* lds, const Gemm g, const Sched& S, const Epi& E) {
;     ...
;       PG8_WAIT_V(8); PG8_WAIT_L(0); PG8_BAR; PG8_MMA(1, 0, At, B0); PG8_MMA(1, 1, At, B1); PG8_BAR; PG8_SCHED;
;       PG8_LDB(B0, 1, 0); PG8_LDB(B1, 1, 1); PG8_SCHED; PG8_LDA(At, 1, 0); PG8_STAGE(PG8_SA(0, 1), a2 + hstepA, voffA);
;       PG8_WAIT_V(8); PG8_WAIT_L(0); PG8_BAR; PG8_MMA(0, 0, At, B0); PG8_MMA(0, 1, At, B1); PG8_BAR; PG8_SCHED;
;       PG8_LDA(At, 1, 1); PG8_STAGE(PG8_SB(1, 0), b3, voffB); PG8_STAGE(PG8_SB(1, 1), b3 + hstepB, voffB); PG8_STAGE(PG8_SA(1, 0), a3, voffA);
;       PG8_WAIT_V(8); PG8_WAIT_L(0); PG8_BAR; PG8_MMA(1, 0, At, B0); PG8_MMA(1, 1, At, B1); PG8_BAR; PG8_SCHED;
	s_setprio 1
	s_waitcnt lgkmcnt(0)
	v_mfma_f32_16x16x32_bf16 v[60:63], v[128:131], v[180:183], v[60:63]
	v_mfma_f32_16x16x32_bf16 v[56:59], v[136:139], v[180:183], v[56:59]
	v_mfma_f32_16x16x32_bf16 v[44:47], v[128:131], v[188:191], v[44:47]
	v_mfma_f32_16x16x32_bf16 v[40:43], v[136:139], v[188:191], v[40:43]
	v_mfma_f32_16x16x32_bf16 v[28:31], v[128:131], v[196:199], v[28:31]
	v_mfma_f32_16x16x32_bf16 v[24:27], v[136:139], v[196:199], v[24:27]
	v_mfma_f32_16x16x32_bf16 v[12:15], v[128:131], v[204:207], v[12:15]
	v_mfma_f32_16x16x32_bf16 v[8:11], v[136:139], v[204:207], v[8:11]
	v_mfma_f32_16x16x32_bf16 v[60:63], v[132:135], v[184:187], v[60:63]
	v_mfma_f32_16x16x32_bf16 v[56:59], v[140:143], v[184:187], v[56:59]
	v_mfma_f32_16x16x32_bf16 v[44:47], v[132:135], v[192:195], v[44:47]
	v_mfma_f32_16x16x32_bf16 v[40:43], v[140:143], v[192:195], v[40:43]
	v_mfma_f32_16x16x32_bf16 v[28:31], v[132:135], v[200:203], v[28:31]
	v_mfma_f32_16x16x32_bf16 v[24:27], v[140:143], v[200:203], v[24:27]
	v_mfma_f32_16x16x32_bf16 v[12:15], v[132:135], v[208:211], v[12:15]
	v_mfma_f32_16x16x32_bf16 v[8:11], v[140:143], v[208:211], v[8:11]
	s_setprio 0
	s_setprio 1
	v_mfma_f32_16x16x32_bf16 v[52:55], v[158:161], v[180:183], v[52:55]
	v_mfma_f32_16x16x32_bf16 v[48:51], v[172:175], v[180:183], v[48:51]
	v_mfma_f32_16x16x32_bf16 v[36:39], v[158:161], v[188:191], v[36:39]
	v_mfma_f32_16x16x32_bf16 v[32:35], v[172:175], v[188:191], v[32:35]
	v_mfma_f32_16x16x32_bf16 v[20:23], v[158:161], v[196:199], v[20:23]
	v_mfma_f32_16x16x32_bf16 v[16:19], v[172:175], v[196:199], v[16:19]
	v_mfma_f32_16x16x32_bf16 v[4:7], v[158:161], v[204:207], v[4:7]
	v_mfma_f32_16x16x32_bf16 v[0:3], v[172:175], v[204:207], v[0:3]
	v_mfma_f32_16x16x32_bf16 v[52:55], v[162:165], v[184:187], v[52:55]
	v_mfma_f32_16x16x32_bf16 v[48:51], v[176:179], v[184:187], v[48:51]
	v_mfma_f32_16x16x32_bf16 v[36:39], v[162:165], v[192:195], v[36:39]
	v_mfma_f32_16x16x32_bf16 v[32:35], v[176:179], v[192:195], v[32:35]
	v_mfma_f32_16x16x32_bf16 v[20:23], v[162:165], v[200:203], v[20:23]
	v_mfma_f32_16x16x32_bf16 v[16:19], v[176:179], v[200:203], v[16:19]
	v_mfma_f32_16x16x32_bf16 v[4:7], v[162:165], v[208:211], v[4:7]
	v_mfma_f32_16x16x32_bf16 v[0:3], v[176:179], v[208:211], v[0:3]
	s_setprio 0
	s_barrier
	s_add_i32 s33, s41, 0x110
	v_add_u32_e32 v140, s33, v166
	ds_read_b128 v[128:131], v140
	ds_read_b128 v[132:135], v140 offset:1024
	ds_read_b128 v[136:139], v140 offset:2048
	ds_read_b128 v[140:143], v140 offset:3072
	ds_read_b128 v[158:161], v171
	ds_read_b128 v[162:165], v171 offset:1024
	ds_read_b128 v[172:175], v171 offset:2048
	ds_read_b128 v[176:179], v171 offset:3072
	s_add_u32 s16, s34, 0x40000
	s_addc_u32 s17, s35, 0
	s_mov_b32 m0, s37
	v_lshl_add_u64 v[222:223], s[16:17], 0, v[144:145]
	ds_read_b128 v[180:183], v169 offset:32768
	ds_read_b128 v[184:187], v169 offset:33792
	ds_read_b128 v[188:191], v169 offset:34816
	ds_read_b128 v[192:195], v169 offset:35840
	ds_read_b128 v[196:199], v169 offset:36864
	ds_read_b128 v[200:203], v169 offset:37888
	ds_read_b128 v[204:207], v169 offset:38912
	ds_read_b128 v[208:211], v169 offset:39936
	global_load_lds_dwordx4 v[222:223], off
	v_lshl_add_u64 v[222:223], s[16:17], 0, v[148:149]
	s_mov_b32 m0, s38
	s_nop 0
	global_load_lds_dwordx4 v[222:223], off
	s_waitcnt vmcnt(8)
	s_waitcnt lgkmcnt(0)
	s_barrier
	s_setprio 1
	s_waitcnt lgkmcnt(0)
	v_mfma_f32_16x16x32_bf16 v[124:127], v[128:131], v[180:183], v[124:127]
	v_mfma_f32_16x16x32_bf16 v[120:123], v[136:139], v[180:183], v[120:123]
	v_mfma_f32_16x16x32_bf16 v[108:111], v[128:131], v[188:191], v[108:111]
	v_mfma_f32_16x16x32_bf16 v[104:107], v[136:139], v[188:191], v[104:107]
	v_mfma_f32_16x16x32_bf16 v[92:95], v[128:131], v[196:199], v[92:95]
	v_mfma_f32_16x16x32_bf16 v[88:91], v[136:139], v[196:199], v[88:91]
	v_mfma_f32_16x16x32_bf16 v[76:79], v[128:131], v[204:207], v[76:79]
	v_mfma_f32_16x16x32_bf16 v[72:75], v[136:139], v[204:207], v[72:75]
	v_mfma_f32_16x16x32_bf16 v[124:127], v[132:135], v[184:187], v[124:127]
	v_mfma_f32_16x16x32_bf16 v[120:123], v[140:143], v[184:187], v[120:123]
	v_mfma_f32_16x16x32_bf16 v[108:111], v[132:135], v[192:195], v[108:111]
	v_mfma_f32_16x16x32_bf16 v[104:107], v[140:143], v[192:195], v[104:107]
	v_mfma_f32_16x16x32_bf16 v[92:95], v[132:135], v[200:203], v[92:95]
	v_mfma_f32_16x16x32_bf16 v[88:91], v[140:143], v[200:203], v[88:91]
	v_mfma_f32_16x16x32_bf16 v[76:79], v[132:135], v[208:211], v[76:79]
	v_mfma_f32_16x16x32_bf16 v[72:75], v[140:143], v[208:211], v[72:75]
	s_setprio 0
	s_setprio 1
	v_mfma_f32_16x16x32_bf16 v[116:119], v[158:161], v[180:183], v[116:119]
	v_mfma_f32_16x16x32_bf16 v[112:115], v[172:175], v[180:183], v[112:115]
	v_mfma_f32_16x16x32_bf16 v[100:103], v[158:161], v[188:191], v[100:103]
	v_mfma_f32_16x16x32_bf16 v[96:99], v[172:175], v[188:191], v[96:99]
	v_mfma_f32_16x16x32_bf16 v[84:87], v[158:161], v[196:199], v[84:87]
	v_mfma_f32_16x16x32_bf16 v[80:83], v[172:175], v[196:199], v[80:83]
	v_mfma_f32_16x16x32_bf16 v[68:71], v[158:161], v[204:207], v[68:71]
	v_mfma_f32_16x16x32_bf16 v[64:67], v[172:175], v[204:207], v[64:67]
	v_mfma_f32_16x16x32_bf16 v[116:119], v[162:165], v[184:187], v[116:119]
	v_mfma_f32_16x16x32_bf16 v[112:115], v[176:179], v[184:187], v[112:115]
	v_mfma_f32_16x16x32_bf16 v[100:103], v[162:165], v[192:195], v[100:103]
	v_mfma_f32_16x16x32_bf16 v[96:99], v[176:179], v[192:195], v[96:99]
	v_mfma_f32_16x16x32_bf16 v[84:87], v[162:165], v[200:203], v[84:87]
	v_mfma_f32_16x16x32_bf16 v[80:83], v[176:179], v[200:203], v[80:83]
	v_mfma_f32_16x16x32_bf16 v[68:71], v[162:165], v[208:211], v[68:71]
	v_mfma_f32_16x16x32_bf16 v[64:67], v[176:179], v[208:211], v[64:67]
	s_setprio 0
	s_barrier
; #define PG8_STAGE(bufoff, gbase, voff) do { _Pragma("unroll") for (int _i = 0; _i < 2; ++_i) \
;     __builtin_amdgcn_global_load_lds((const unsigned*)((const char*)(gbase) + (voff)[_i]), (PG8_LAS unsigned*)(lds + (bufoff) + ldsw + _i * 8192), 16, 0, 0); } while (0)
; #define PG8_LDA(dst, b, h) do { _Pragma("unroll") for (int m = 0; m < 4; ++m) _Pragma("unroll") for (int k = 0; k < 2; ++k) dst[m][k] = *(const PG8_LAS bf16x8*)(lds + PG8_SA(b, h) + aoff + m * 2048 + k * 1024); } while (0)
; #define PG8_MMA(ai, bj, At, Bt) do { __builtin_amdgcn_s_setprio(1); _Pragma("unroll") for (int m = 0; m < 4; ++m) _Pragma("unroll") for (int n = 0; n < 2; ++n) _Pragma("unroll") for (int k = 0; k < 2; ++k) \
;     acc[ai][bj][m][n] = __builtin_amdgcn_mfma_f32_16x16x32_bf16(Bt[n][k], At[m][k], acc[ai][bj][m][n], 0, 0, 0); __builtin_amdgcn_s_setprio(0); } while (0)
; #define PG8_WAIT_V(n) asm volatile("s_waitcnt vmcnt(" #n ")" ::: "memory")
; #define PG8_WAIT_L(n) asm volatile("s_waitcnt lgkmcnt(" #n ")" ::: "memory")
; #define PG8_BAR __builtin_amdgcn_s_barrier()
; #define PG8_SCHED __builtin_amdgcn_sched_barrier(0)
;   DI void operator()(const f32x4 (&acc)[2][2][4][2], const Unit& u, int wr, int wc, int fr, int fq) const {
;     ...
;     RES_LD(0)
; #pragma unroll
;     for (int i = 0; i < 8; ++i) {
;       const int ai = i >> 2, m = i & 3;
;       if (i + 1 < 8) RES_LD(i + 1)
; template <class Epi, class Sched>
; DI void gemm_phase(PG8_LAS unsigned char* lds, const Gemm g, const Sched& S, const Epi& E) {
;     ...
;       PG8_WAIT_V(8); PG8_WAIT_L(0); PG8_BAR; PG8_MMA(0, 0, At, B0); PG8_MMA(0, 1, At, B1); PG8_BAR; PG8_SCHED;
;       PG8_LDA(At, 1, 1); PG8_STAGE(PG8_SB(1, 0), b3, voffB); PG8_STAGE(PG8_SB(1, 1), b3 + hstepB, voffB); PG8_STAGE(PG8_SA(1, 0), a3, voffA);
;       PG8_WAIT_V(8); PG8_WAIT_L(0); PG8_BAR; PG8_MMA(1, 0, At, B0); PG8_MMA(1, 1, At, B1); PG8_BAR; PG8_SCHED;
;     }
;     if (wr == 0) PG8_BAR;
	s_add_i32 s16, s33, s2
	v_lshl_add_u64 v[214:215], v[214:215], 0, s[8:9]
	s_mov_b32 m0, s16
	ds_read_b128 v[180:183], v169 offset:49152
	ds_read_b128 v[184:187], v169 offset:50176
	ds_read_b128 v[188:191], v169 offset:51200
	ds_read_b128 v[192:195], v169 offset:52224
	ds_read_b128 v[196:199], v169 offset:53248
	ds_read_b128 v[200:203], v169 offset:54272
	ds_read_b128 v[204:207], v169 offset:55296
	ds_read_b128 v[208:211], v169 offset:56320
	global_load_lds_dwordx4 v[214:215], off
	s_add_i32 m0, s16, 0x2000
	s_add_u32 s16, s30, 0x40080
	v_lshl_add_u64 v[214:215], v[216:217], 0, s[8:9]
	s_addc_u32 s17, s31, 0
	s_add_i32 s30, s65, s2
	global_load_lds_dwordx4 v[214:215], off
	v_lshl_add_u64 v[214:215], s[16:17], 0, v[146:147]
	s_mov_b32 m0, s30
	s_nop 0
	global_load_lds_dwordx4 v[214:215], off
	v_lshl_add_u64 v[214:215], s[16:17], 0, v[150:151]
	s_add_i32 m0, s30, 0x2000
	s_nop 0
	global_load_lds_dwordx4 v[214:215], off
	v_lshl_add_u64 v[214:215], v[218:219], 0, s[8:9]
	s_mov_b32 m0, s4
	s_nop 0
	global_load_lds_dwordx4 v[214:215], off
	v_lshl_add_u64 v[214:215], v[220:221], 0, s[8:9]
	s_mov_b32 m0, s5
	s_nop 0
	global_load_lds_dwordx4 v[214:215], off
	s_waitcnt vmcnt(8)
	s_waitcnt lgkmcnt(0)
	s_barrier
	s_setprio 1
	s_waitcnt lgkmcnt(0)
	v_mfma_f32_16x16x32_bf16 v[60:63], v[128:131], v[180:183], v[60:63]
	v_mfma_f32_16x16x32_bf16 v[56:59], v[136:139], v[180:183], v[56:59]
	v_mfma_f32_16x16x32_bf16 v[44:47], v[128:131], v[188:191], v[44:47]
	v_mfma_f32_16x16x32_bf16 v[40:43], v[136:139], v[188:191], v[40:43]
	v_mfma_f32_16x16x32_bf16 v[28:31], v[128:131], v[196:199], v[28:31]
	v_mfma_f32_16x16x32_bf16 v[24:27], v[136:139], v[196:199], v[24:27]
	v_mfma_f32_16x16x32_bf16 v[12:15], v[128:131], v[204:207], v[12:15]
	v_mfma_f32_16x16x32_bf16 v[8:11], v[136:139], v[204:207], v[8:11]
	v_mfma_f32_16x16x32_bf16 v[60:63], v[132:135], v[184:187], v[60:63]
	v_mfma_f32_16x16x32_bf16 v[56:59], v[140:143], v[184:187], v[56:59]
	v_mfma_f32_16x16x32_bf16 v[44:47], v[132:135], v[192:195], v[44:47]
	v_mfma_f32_16x16x32_bf16 v[40:43], v[140:143], v[192:195], v[40:43]
	v_mfma_f32_16x16x32_bf16 v[28:31], v[132:135], v[200:203], v[28:31]
	v_mfma_f32_16x16x32_bf16 v[24:27], v[140:143], v[200:203], v[24:27]
	v_mfma_f32_16x16x32_bf16 v[12:15], v[132:135], v[208:211], v[12:15]
	v_mfma_f32_16x16x32_bf16 v[8:11], v[140:143], v[208:211], v[8:11]
	s_setprio 0
	s_setprio 1
	v_mfma_f32_16x16x32_bf16 v[52:55], v[158:161], v[180:183], v[52:55]
	v_mfma_f32_16x16x32_bf16 v[48:51], v[172:175], v[180:183], v[48:51]
	v_mfma_f32_16x16x32_bf16 v[36:39], v[158:161], v[188:191], v[36:39]
	v_mfma_f32_16x16x32_bf16 v[32:35], v[172:175], v[188:191], v[32:35]
	v_mfma_f32_16x16x32_bf16 v[20:23], v[158:161], v[196:199], v[20:23]
	v_mfma_f32_16x16x32_bf16 v[16:19], v[172:175], v[196:199], v[16:19]
	v_mfma_f32_16x16x32_bf16 v[4:7], v[158:161], v[204:207], v[4:7]
	v_mfma_f32_16x16x32_bf16 v[0:3], v[172:175], v[204:207], v[0:3]
	v_mfma_f32_16x16x32_bf16 v[52:55], v[162:165], v[184:187], v[52:55]
	v_mfma_f32_16x16x32_bf16 v[48:51], v[176:179], v[184:187], v[48:51]
	v_mfma_f32_16x16x32_bf16 v[36:39], v[162:165], v[192:195], v[36:39]
	v_mfma_f32_16x16x32_bf16 v[32:35], v[176:179], v[192:195], v[32:35]
	v_mfma_f32_16x16x32_bf16 v[20:23], v[162:165], v[200:203], v[20:23]
	v_mfma_f32_16x16x32_bf16 v[16:19], v[176:179], v[200:203], v[16:19]
	v_mfma_f32_16x16x32_bf16 v[4:7], v[162:165], v[208:211], v[4:7]
	v_mfma_f32_16x16x32_bf16 v[0:3], v[176:179], v[208:211], v[0:3]
	s_setprio 0
	s_barrier
	s_add_i32 s70, s70, 2
	s_add_u32 s28, s28, 0x100
	s_addc_u32 s29, s29, 0
	s_add_u32 s68, s68, 0x100
	s_addc_u32 s69, s69, 0
	s_cmp_gt_u32 s70, 13
	s_cbranch_scc0 .LBB0_563
	v_lshl_add_u32 v164, s26, 8, v153
	v_ashrrev_i32_e32 v165, 31, v164
	s_lshl_b32 s16, s12, 8
	v_lshlrev_b64 v[128:129], 10, v[164:165]
	s_ashr_i32 s17, s16, 31
	v_lshl_add_u64 v[186:187], v[128:129], 0, s[16:17]
	v_or_b32_e32 v186, v186, v152
	v_lshl_add_u64 v[162:163], v[186:187], 2, s[44:45]
	s_mov_b64 s[16:17], 0x10000
	v_add_co_u32_e32 v130, vcc, s39, v162
	global_load_dwordx4 v[158:161], v[162:163], off offset:16
	global_load_dwordx4 v[174:177], v[162:163], off
	global_load_dwordx4 v[178:181], v[162:163], off offset:528
	global_load_dwordx4 v[182:185], v[162:163], off offset:512
	v_lshl_add_u64 v[128:129], v[162:163], 0, s[16:17]
	v_addc_co_u32_e32 v131, vcc, 0, v163, vcc
	s_mov_b64 s[16:17], 0x10200
	global_load_dwordx4 v[140:143], v[130:131], off
	global_load_dwordx4 v[136:139], v[128:129], off offset:16
	v_lshl_add_u64 v[128:129], v[162:163], 0, s[16:17]
	global_load_dwordx4 v[132:135], v[130:131], off offset:512
	s_nop 0
	global_load_dwordx4 v[128:131], v[128:129], off offset:16
	s_mov_b32 s100, 0x20000
	s_mov_b32 s101, 0
	v_lshl_add_u64 v[226:227], v[162:163], 0, s[100:101]
	global_load_dwordx4 v[228:231], v[226:227], off
	global_load_dwordx4 v[228:231], v[226:227], off offset:512
	s_mov_b32 s100, 0x30000
	s_mov_b32 s101, 0
	v_lshl_add_u64 v[226:227], v[162:163], 0, s[100:101]
	global_load_dwordx4 v[228:231], v[226:227], off
	global_load_dwordx4 v[228:231], v[226:227], off offset:512
	s_mov_b32 s100, 0x80000
	s_mov_b32 s101, 0
	v_lshl_add_u64 v[226:227], v[162:163], 0, s[100:101]
	global_load_dwordx4 v[228:231], v[226:227], off
	global_load_dwordx4 v[228:231], v[226:227], off offset:512
	s_mov_b32 s100, 0x90000
	s_mov_b32 s101, 0
	v_lshl_add_u64 v[226:227], v[162:163], 0, s[100:101]
	global_load_dwordx4 v[228:231], v[226:227], off
	global_load_dwordx4 v[228:231], v[226:227], off offset:512
	s_mov_b32 s100, 0xa0000
	s_mov_b32 s101, 0
	v_lshl_add_u64 v[226:227], v[162:163], 0, s[100:101]
	global_load_dwordx4 v[228:231], v[226:227], off
	global_load_dwordx4 v[228:231], v[226:227], off offset:512
	s_mov_b32 s100, 0xb0000
	s_mov_b32 s101, 0
	v_lshl_add_u64 v[226:227], v[162:163], 0, s[100:101]
	global_load_dwordx4 v[228:231], v[226:227], off
	global_load_dwordx4 v[228:231], v[226:227], off offset:512
	s_and_b64 vcc, exec, s[10:11]
	s_cbranch_vccz .LBB0_566
	s_barrier

; #define PG8_STAGE(bufoff, gbase, voff) do { _Pragma("unroll") for (int _i = 0; _i < 2; ++_i) \
;     __builtin_amdgcn_global_load_lds((const unsigned*)((const char*)(gbase) + (voff)[_i]), (PG8_LAS unsigned*)(lds + (bufoff) + ldsw + _i * 8192), 16, 0, 0); } while (0)
; #define PG8_LDA(dst, b, h) do { _Pragma("unroll") for (int m = 0; m < 4; ++m) _Pragma("unroll") for (int k = 0; k < 2; ++k) dst[m][k] = *(const PG8_LAS bf16x8*)(lds + PG8_SA(b, h) + aoff + m * 2048 + k * 1024); } while (0)
; #define PG8_LDB(dst, b, h) do { _Pragma("unroll") for (int n = 0; n < 2; ++n) _Pragma("unroll") for (int k = 0; k < 2; ++k) dst[n][k] = *(const PG8_LAS bf16x8*)(lds + PG8_SB(b, h) + boff + n * 2048 + k * 1024); } while (0)
; #define PG8_MMA(ai, bj, At, Bt) do { __builtin_amdgcn_s_setprio(1); _Pragma("unroll") for (int m = 0; m < 4; ++m) _Pragma("unroll") for (int n = 0; n < 2; ++n) _Pragma("unroll") for (int k = 0; k < 2; ++k) \
;     acc[ai][bj][m][n] = __builtin_amdgcn_mfma_f32_16x16x32_bf16(Bt[n][k], At[m][k], acc[ai][bj][m][n], 0, 0, 0); __builtin_amdgcn_s_setprio(0); } while (0)
; #define PG8_WAIT_V(n) asm volatile("s_waitcnt vmcnt(" #n ")" ::: "memory")
; #define PG8_WAIT_L(n) asm volatile("s_waitcnt lgkmcnt(" #n ")" ::: "memory")
; #define PG8_BAR __builtin_amdgcn_s_barrier()
; #define PG8_SCHED __builtin_amdgcn_sched_barrier(0)
; template <class Epi, class Sched>
; DI void gemm_phase(PG8_LAS unsigned char* lds, const Gemm g, const Sched& S, const Epi& E) {
;     ...
;       PG8_LDB(B0, 0, 0); PG8_LDB(B1, 0, 1); PG8_SCHED; PG8_LDA(At, 0, 0); PG8_STAGE(PG8_SA(1, 1), a1 + hstepA, voffA);
;       PG8_WAIT_V(8); PG8_WAIT_L(0); PG8_BAR; PG8_MMA(0, 0, At, B0); PG8_MMA(0, 1, At, B1); PG8_BAR; PG8_SCHED;
;       PG8_LDA(At, 0, 1); PG8_STAGE(PG8_SB(0, 0), b2, voffB); PG8_STAGE(PG8_SB(0, 1), b2 + hstepB, voffB); PG8_STAGE(PG8_SA(0, 0), a2, voffA);
;       PG8_WAIT_V(8); PG8_WAIT_L(0); PG8_BAR; PG8_MMA(1, 0, At, B0); PG8_MMA(1, 1, At, B1); PG8_BAR; PG8_SCHED;
.LBB0_721:
	ds_read_b128 v[128:131], v156
	ds_read_b128 v[132:135], v156 offset:1024
	ds_read_b128 v[150:153], v156 offset:2048
	ds_read_b128 v[162:165], v156 offset:3072
	ds_read_b128 v[166:169], v157
	ds_read_b128 v[170:173], v157 offset:1024
	ds_read_b128 v[174:177], v157 offset:2048
	ds_read_b128 v[178:181], v157 offset:3072
	s_add_u32 s26, s24, 0x100
	s_addc_u32 s27, s25, 0
	s_cmp_eq_u32 s65, 40
	s_cselect_b32 s31, s21, s27
	s_cselect_b32 s30, s20, s26
	s_cselect_b32 s29, s23, s64
	s_cselect_b32 s28, s22, s55
	v_lshl_add_u64 v[210:211], s[24:25], 0, v[146:147]
	s_add_i32 m0, s3, 0xc000
	ds_read_b128 v[182:185], v158
	ds_read_b128 v[186:189], v158 offset:1024
	ds_read_b128 v[190:193], v158 offset:2048
	ds_read_b128 v[194:197], v158 offset:3072
	ds_read_b128 v[198:201], v158 offset:4096
	ds_read_b128 v[202:205], v158 offset:5120
	ds_read_b128 v[206:209], v158 offset:6144
	ds_read_b128 v[214:217], v158 offset:7168
	global_load_lds_dwordx4 v[210:211], off
	v_lshl_add_u64 v[210:211], s[24:25], 0, v[148:149]
	s_add_i32 m0, s3, 0xe000
	s_nop 0
	global_load_lds_dwordx4 v[210:211], off
	s_waitcnt vmcnt(8)
	s_waitcnt lgkmcnt(0)
	s_barrier
	s_setprio 1
	s_waitcnt lgkmcnt(0)
	v_mfma_f32_16x16x32_bf16 v[124:127], v[128:131], v[182:185], v[124:127]
	v_mfma_f32_16x16x32_bf16 v[120:123], v[150:153], v[182:185], v[120:123]
	v_mfma_f32_16x16x32_bf16 v[108:111], v[128:131], v[190:193], v[108:111]
	v_mfma_f32_16x16x32_bf16 v[104:107], v[150:153], v[190:193], v[104:107]
	v_mfma_f32_16x16x32_bf16 v[92:95], v[128:131], v[198:201], v[92:95]
	v_mfma_f32_16x16x32_bf16 v[88:91], v[150:153], v[198:201], v[88:91]
	v_mfma_f32_16x16x32_bf16 v[76:79], v[128:131], v[206:209], v[76:79]
	v_mfma_f32_16x16x32_bf16 v[72:75], v[150:153], v[206:209], v[72:75]
	v_mfma_f32_16x16x32_bf16 v[124:127], v[132:135], v[186:189], v[124:127]
	v_mfma_f32_16x16x32_bf16 v[120:123], v[162:165], v[186:189], v[120:123]
	v_mfma_f32_16x16x32_bf16 v[108:111], v[132:135], v[194:197], v[108:111]
	v_mfma_f32_16x16x32_bf16 v[104:107], v[162:165], v[194:197], v[104:107]
	v_mfma_f32_16x16x32_bf16 v[92:95], v[132:135], v[202:205], v[92:95]
	v_mfma_f32_16x16x32_bf16 v[88:91], v[162:165], v[202:205], v[88:91]
	v_mfma_f32_16x16x32_bf16 v[76:79], v[132:135], v[214:217], v[76:79]
	v_mfma_f32_16x16x32_bf16 v[72:75], v[162:165], v[214:217], v[72:75]
	s_setprio 0
	s_setprio 1
	v_mfma_f32_16x16x32_bf16 v[116:119], v[166:169], v[182:185], v[116:119]
	v_mfma_f32_16x16x32_bf16 v[112:115], v[174:177], v[182:185], v[112:115]
	v_mfma_f32_16x16x32_bf16 v[100:103], v[166:169], v[190:193], v[100:103]
	v_mfma_f32_16x16x32_bf16 v[96:99], v[174:177], v[190:193], v[96:99]
	v_mfma_f32_16x16x32_bf16 v[84:87], v[166:169], v[198:201], v[84:87]
	v_mfma_f32_16x16x32_bf16 v[80:83], v[174:177], v[198:201], v[80:83]
	v_mfma_f32_16x16x32_bf16 v[68:71], v[166:169], v[206:209], v[68:71]
	v_mfma_f32_16x16x32_bf16 v[64:67], v[174:177], v[206:209], v[64:67]
	v_mfma_f32_16x16x32_bf16 v[116:119], v[170:173], v[186:189], v[116:119]
	v_mfma_f32_16x16x32_bf16 v[112:115], v[178:181], v[186:189], v[112:115]
	v_mfma_f32_16x16x32_bf16 v[100:103], v[170:173], v[194:197], v[100:103]
	v_mfma_f32_16x16x32_bf16 v[96:99], v[178:181], v[194:197], v[96:99]
	v_mfma_f32_16x16x32_bf16 v[84:87], v[170:173], v[202:205], v[84:87]
	v_mfma_f32_16x16x32_bf16 v[80:83], v[178:181], v[202:205], v[80:83]
	v_mfma_f32_16x16x32_bf16 v[68:71], v[170:173], v[214:217], v[68:71]
	v_mfma_f32_16x16x32_bf16 v[64:67], v[178:181], v[214:217], v[64:67]
	s_setprio 0
	s_barrier
	s_add_i32 s16, s37, s2
	v_lshl_add_u64 v[210:211], s[28:29], 0, v[138:139]
	s_mov_b32 m0, s16
	ds_read_b128 v[182:185], v158 offset:16384
	ds_read_b128 v[186:189], v158 offset:17408
	ds_read_b128 v[190:193], v158 offset:18432
	ds_read_b128 v[194:197], v158 offset:19456
	ds_read_b128 v[198:201], v158 offset:20480
	ds_read_b128 v[202:205], v158 offset:21504
	ds_read_b128 v[206:209], v158 offset:22528
	ds_read_b128 v[214:217], v158 offset:23552
	global_load_lds_dwordx4 v[210:211], off
	s_add_i32 m0, s16, 0x2000
	s_add_u32 s16, s28, 0xb0000
	v_lshl_add_u64 v[218:219], s[28:29], 0, v[142:143]
	s_addc_u32 s17, s29, 0
	s_add_i32 s24, s38, s2
	global_load_lds_dwordx4 v[218:219], off
	v_lshl_add_u64 v[220:221], s[16:17], 0, v[138:139]
	s_mov_b32 m0, s24
	v_lshl_add_u64 v[222:223], s[30:31], 0, v[140:141]
	global_load_lds_dwordx4 v[220:221], off
	v_lshl_add_u64 v[220:221], s[16:17], 0, v[142:143]
	s_add_i32 m0, s24, 0x2000
	s_nop 0
	global_load_lds_dwordx4 v[220:221], off
	v_lshl_add_u64 v[220:221], s[30:31], 0, v[136:137]
	s_mov_b32 m0, s3
	s_nop 0
	global_load_lds_dwordx4 v[220:221], off
	s_mov_b32 m0, s34
	s_nop 0
	global_load_lds_dwordx4 v[222:223], off
	s_waitcnt vmcnt(8)
	s_waitcnt lgkmcnt(0)
	s_barrier
; #define PG8_STAGE(bufoff, gbase, voff) do { _Pragma("unroll") for (int _i = 0; _i < 2; ++_i) \
;     __builtin_amdgcn_global_load_lds((const unsigned*)((const char*)(gbase) + (voff)[_i]), (PG8_LAS unsigned*)(lds + (bufoff) + ldsw + _i * 8192), 16, 0, 0); } while (0)
; #define PG8_LDA(dst, b, h) do { _Pragma("unroll") for (int m = 0; m < 4; ++m) _Pragma("unroll") for (int k = 0; k < 2; ++k) dst[m][k] = *(const PG8_LAS bf16x8*)(lds + PG8_SA(b, h) + aoff + m * 2048 + k * 1024); } while (0)
; #define PG8_LDB(dst, b, h) do { _Pragma("unroll") for (int n = 0; n < 2; ++n) _Pragma("unroll") for (int k = 0; k < 2; ++k) dst[n][k] = *(const PG8_LAS bf16x8*)(lds + PG8_SB(b, h) + boff + n * 2048 + k * 1024); } while (0)
; #define PG8_MMA(ai, bj, At, Bt) do { __builtin_amdgcn_s_setprio(1); _Pragma("unroll") for (int m = 0; m < 4; ++m) _Pragma("unroll") for (int n = 0; n < 2; ++n) _Pragma("unroll") for (int k = 0; k < 2; ++k) \
;     acc[ai][bj][m][n] = __builtin_amdgcn_mfma_f32_16x16x32_bf16(Bt[n][k], At[m][k], acc[ai][bj][m][n], 0, 0, 0); __builtin_amdgcn_s_setprio(0); } while (0)
; #define PG8_WAIT_V(n) asm volatile("s_waitcnt vmcnt(" #n ")" ::: "memory")
; #define PG8_WAIT_L(n) asm volatile("s_waitcnt lgkmcnt(" #n ")" ::: "memory")
; #define PG8_BAR __builtin_amdgcn_s_barrier()
; #define PG8_SCHED __builtin_amdgcn_sched_barrier(0)
; template <class Epi, class Sched>
; DI void gemm_phase(PG8_LAS unsigned char* lds, const Gemm g, const Sched& S, const Epi& E) {
;     ...
;       PG8_WAIT_V(8); PG8_WAIT_L(0); PG8_BAR; PG8_MMA(1, 0, At, B0); PG8_MMA(1, 1, At, B1); PG8_BAR; PG8_SCHED;
;       PG8_LDB(B0, 1, 0); PG8_LDB(B1, 1, 1); PG8_SCHED; PG8_LDA(At, 1, 0); PG8_STAGE(PG8_SA(0, 1), a2 + hstepA, voffA);
;       PG8_WAIT_V(8); PG8_WAIT_L(0); PG8_BAR; PG8_MMA(0, 0, At, B0); PG8_MMA(0, 1, At, B1); PG8_BAR; PG8_SCHED;
;       PG8_LDA(At, 1, 1); PG8_STAGE(PG8_SB(1, 0), b3, voffB); PG8_STAGE(PG8_SB(1, 1), b3 + hstepB, voffB); PG8_STAGE(PG8_SA(1, 0), a3, voffA);
;       PG8_WAIT_V(8); PG8_WAIT_L(0); PG8_BAR; PG8_MMA(1, 0, At, B0); PG8_MMA(1, 1, At, B1); PG8_BAR; PG8_SCHED;
	s_setprio 1
	s_waitcnt lgkmcnt(0)
	v_mfma_f32_16x16x32_bf16 v[60:63], v[128:131], v[182:185], v[60:63]
	v_mfma_f32_16x16x32_bf16 v[56:59], v[150:153], v[182:185], v[56:59]
	v_mfma_f32_16x16x32_bf16 v[44:47], v[128:131], v[190:193], v[44:47]
	v_mfma_f32_16x16x32_bf16 v[40:43], v[150:153], v[190:193], v[40:43]
	v_mfma_f32_16x16x32_bf16 v[28:31], v[128:131], v[198:201], v[28:31]
	v_mfma_f32_16x16x32_bf16 v[24:27], v[150:153], v[198:201], v[24:27]
	v_mfma_f32_16x16x32_bf16 v[12:15], v[128:131], v[206:209], v[12:15]
	v_mfma_f32_16x16x32_bf16 v[8:11], v[150:153], v[206:209], v[8:11]
	v_mfma_f32_16x16x32_bf16 v[60:63], v[132:135], v[186:189], v[60:63]
	v_mfma_f32_16x16x32_bf16 v[56:59], v[162:165], v[186:189], v[56:59]
	v_mfma_f32_16x16x32_bf16 v[44:47], v[132:135], v[194:197], v[44:47]
	v_mfma_f32_16x16x32_bf16 v[40:43], v[162:165], v[194:197], v[40:43]
	v_mfma_f32_16x16x32_bf16 v[28:31], v[132:135], v[202:205], v[28:31]
	v_mfma_f32_16x16x32_bf16 v[24:27], v[162:165], v[202:205], v[24:27]
	v_mfma_f32_16x16x32_bf16 v[12:15], v[132:135], v[214:217], v[12:15]
	v_mfma_f32_16x16x32_bf16 v[8:11], v[162:165], v[214:217], v[8:11]
	s_setprio 0
	s_setprio 1
	v_mfma_f32_16x16x32_bf16 v[52:55], v[166:169], v[182:185], v[52:55]
	v_mfma_f32_16x16x32_bf16 v[48:51], v[174:177], v[182:185], v[48:51]
	v_mfma_f32_16x16x32_bf16 v[36:39], v[166:169], v[190:193], v[36:39]
	v_mfma_f32_16x16x32_bf16 v[32:35], v[174:177], v[190:193], v[32:35]
	v_mfma_f32_16x16x32_bf16 v[20:23], v[166:169], v[198:201], v[20:23]
	v_mfma_f32_16x16x32_bf16 v[16:19], v[174:177], v[198:201], v[16:19]
	v_mfma_f32_16x16x32_bf16 v[4:7], v[166:169], v[206:209], v[4:7]
	v_mfma_f32_16x16x32_bf16 v[0:3], v[174:177], v[206:209], v[0:3]
	v_mfma_f32_16x16x32_bf16 v[52:55], v[170:173], v[186:189], v[52:55]
	v_mfma_f32_16x16x32_bf16 v[48:51], v[178:181], v[186:189], v[48:51]
	v_mfma_f32_16x16x32_bf16 v[36:39], v[170:173], v[194:197], v[36:39]
	v_mfma_f32_16x16x32_bf16 v[32:35], v[178:181], v[194:197], v[32:35]
	v_mfma_f32_16x16x32_bf16 v[20:23], v[170:173], v[202:205], v[20:23]
	v_mfma_f32_16x16x32_bf16 v[16:19], v[178:181], v[202:205], v[16:19]
	v_mfma_f32_16x16x32_bf16 v[4:7], v[170:173], v[214:217], v[4:7]
	v_mfma_f32_16x16x32_bf16 v[0:3], v[178:181], v[214:217], v[0:3]
	s_setprio 0
	s_barrier
	s_mov_b32 s16, 0x18000
	s_add_i32 s24, s16, 0x110
	v_add_u32_e32 v161, s24, v155
	ds_read_b128 v[128:131], v161
	ds_read_b128 v[132:135], v161 offset:1024
	ds_read_b128 v[150:153], v161 offset:2048
	ds_read_b128 v[162:165], v161 offset:3072
	ds_read_b128 v[166:169], v160
	ds_read_b128 v[170:173], v160 offset:1024
	ds_read_b128 v[174:177], v160 offset:2048
	ds_read_b128 v[178:181], v160 offset:3072
	s_add_u32 s16, s30, 0xb0000
	s_addc_u32 s17, s31, 0
	s_mov_b32 m0, s18
	v_lshl_add_u64 v[224:225], s[16:17], 0, v[136:137]
	ds_read_b128 v[182:185], v158 offset:32768
	ds_read_b128 v[186:189], v158 offset:33792
	ds_read_b128 v[190:193], v158 offset:34816
	ds_read_b128 v[194:197], v158 offset:35840
	ds_read_b128 v[198:201], v158 offset:36864
	ds_read_b128 v[202:205], v158 offset:37888
	ds_read_b128 v[206:209], v158 offset:38912
	ds_read_b128 v[214:217], v158 offset:39936
	global_load_lds_dwordx4 v[224:225], off
	v_lshl_add_u64 v[224:225], s[16:17], 0, v[140:141]
	s_mov_b32 m0, s19
	s_nop 0
	global_load_lds_dwordx4 v[224:225], off
	s_waitcnt vmcnt(8)
	s_waitcnt lgkmcnt(0)
	s_barrier
	s_setprio 1
	s_waitcnt lgkmcnt(0)
	v_mfma_f32_16x16x32_bf16 v[124:127], v[128:131], v[182:185], v[124:127]
	v_mfma_f32_16x16x32_bf16 v[120:123], v[150:153], v[182:185], v[120:123]
	v_mfma_f32_16x16x32_bf16 v[108:111], v[128:131], v[190:193], v[108:111]
	v_mfma_f32_16x16x32_bf16 v[104:107], v[150:153], v[190:193], v[104:107]
	v_mfma_f32_16x16x32_bf16 v[92:95], v[128:131], v[198:201], v[92:95]
	v_mfma_f32_16x16x32_bf16 v[88:91], v[150:153], v[198:201], v[88:91]
	v_mfma_f32_16x16x32_bf16 v[76:79], v[128:131], v[206:209], v[76:79]
	v_mfma_f32_16x16x32_bf16 v[72:75], v[150:153], v[206:209], v[72:75]
	v_mfma_f32_16x16x32_bf16 v[124:127], v[132:135], v[186:189], v[124:127]
	v_mfma_f32_16x16x32_bf16 v[120:123], v[162:165], v[186:189], v[120:123]
	v_mfma_f32_16x16x32_bf16 v[108:111], v[132:135], v[194:197], v[108:111]
	v_mfma_f32_16x16x32_bf16 v[104:107], v[162:165], v[194:197], v[104:107]
	v_mfma_f32_16x16x32_bf16 v[92:95], v[132:135], v[202:205], v[92:95]
	v_mfma_f32_16x16x32_bf16 v[88:91], v[162:165], v[202:205], v[88:91]
	v_mfma_f32_16x16x32_bf16 v[76:79], v[132:135], v[214:217], v[76:79]
	v_mfma_f32_16x16x32_bf16 v[72:75], v[162:165], v[214:217], v[72:75]
	s_setprio 0
	s_setprio 1
	v_mfma_f32_16x16x32_bf16 v[116:119], v[166:169], v[182:185], v[116:119]
	v_mfma_f32_16x16x32_bf16 v[112:115], v[174:177], v[182:185], v[112:115]
	v_mfma_f32_16x16x32_bf16 v[100:103], v[166:169], v[190:193], v[100:103]
	v_mfma_f32_16x16x32_bf16 v[96:99], v[174:177], v[190:193], v[96:99]
	v_mfma_f32_16x16x32_bf16 v[84:87], v[166:169], v[198:201], v[84:87]
	v_mfma_f32_16x16x32_bf16 v[80:83], v[174:177], v[198:201], v[80:83]
	v_mfma_f32_16x16x32_bf16 v[68:71], v[166:169], v[206:209], v[68:71]
	v_mfma_f32_16x16x32_bf16 v[64:67], v[174:177], v[206:209], v[64:67]
	v_mfma_f32_16x16x32_bf16 v[116:119], v[170:173], v[186:189], v[116:119]
	v_mfma_f32_16x16x32_bf16 v[112:115], v[178:181], v[186:189], v[112:115]
	v_mfma_f32_16x16x32_bf16 v[100:103], v[170:173], v[194:197], v[100:103]
	v_mfma_f32_16x16x32_bf16 v[96:99], v[178:181], v[194:197], v[96:99]
	v_mfma_f32_16x16x32_bf16 v[84:87], v[170:173], v[202:205], v[84:87]
	v_mfma_f32_16x16x32_bf16 v[80:83], v[178:181], v[202:205], v[80:83]
	v_mfma_f32_16x16x32_bf16 v[68:71], v[170:173], v[214:217], v[68:71]
	v_mfma_f32_16x16x32_bf16 v[64:67], v[178:181], v[214:217], v[64:67]
	s_setprio 0
	s_barrier
; #define PG8_MMA(ai, bj, At, Bt) do { __builtin_amdgcn_s_setprio(1); _Pragma("unroll") for (int m = 0; m < 4; ++m) _Pragma("unroll") for (int n = 0; n < 2; ++n) _Pragma("unroll") for (int k = 0; k < 2; ++k) \
;     acc[ai][bj][m][n] = __builtin_amdgcn_mfma_f32_16x16x32_bf16(Bt[n][k], At[m][k], acc[ai][bj][m][n], 0, 0, 0); __builtin_amdgcn_s_setprio(0); } while (0)
; #define PG8_WAIT_V(n) asm volatile("s_waitcnt vmcnt(" #n ")" ::: "memory")
; #define PG8_WAIT_L(n) asm volatile("s_waitcnt lgkmcnt(" #n ")" ::: "memory")
; #define PG8_BAR __builtin_amdgcn_s_barrier()
; #define PG8_SCHED __builtin_amdgcn_sched_barrier(0)
;   DI void operator()(const f32x4 (&acc)[2][2][4][2], const Unit& u, int wr, int wc, int fr, int fq) const {
;     ...
;     RES_LD(0)
; #pragma unroll
;     for (int i = 0; i < 8; ++i) {
;       const int ai = i >> 2, m = i & 3;
;       if (i + 1 < 8) RES_LD(i + 1)
; template <class Epi, class Sched>
; DI void gemm_phase(PG8_LAS unsigned char* lds, const Gemm g, const Sched& S, const Epi& E) {
;     ...
;       PG8_WAIT_V(8); PG8_WAIT_L(0); PG8_BAR; PG8_MMA(1, 0, At, B0); PG8_MMA(1, 1, At, B1); PG8_BAR; PG8_SCHED;
;     }
;     if (wr == 0) PG8_BAR;
	s_add_i32 s16, s24, s2
	v_lshl_add_u64 v[210:211], v[210:211], 0, s[10:11]
	s_mov_b32 m0, s16
	ds_read_b128 v[182:185], v158 offset:49152
	ds_read_b128 v[186:189], v158 offset:50176
	ds_read_b128 v[190:193], v158 offset:51200
	ds_read_b128 v[194:197], v158 offset:52224
	ds_read_b128 v[198:201], v158 offset:53248
	ds_read_b128 v[202:205], v158 offset:54272
	ds_read_b128 v[206:209], v158 offset:55296
	ds_read_b128 v[214:217], v158 offset:56320
	global_load_lds_dwordx4 v[210:211], off
	s_add_i32 m0, s16, 0x2000
	s_add_u32 s16, s28, 0xb0080
	v_lshl_add_u64 v[210:211], v[218:219], 0, s[10:11]
	s_addc_u32 s17, s29, 0
	s_add_i32 s24, s39, s2
	global_load_lds_dwordx4 v[210:211], off
	v_lshl_add_u64 v[210:211], s[16:17], 0, v[138:139]
	s_mov_b32 m0, s24
	s_nop 0
	global_load_lds_dwordx4 v[210:211], off
	v_lshl_add_u64 v[210:211], s[16:17], 0, v[142:143]
	s_add_i32 m0, s24, 0x2000
	s_nop 0
	global_load_lds_dwordx4 v[210:211], off
	v_lshl_add_u64 v[210:211], v[220:221], 0, s[10:11]
	s_mov_b32 m0, s5
	s_nop 0
	global_load_lds_dwordx4 v[210:211], off
	v_lshl_add_u64 v[210:211], v[222:223], 0, s[10:11]
	s_mov_b32 m0, s35
	s_nop 0
	global_load_lds_dwordx4 v[210:211], off
	s_waitcnt vmcnt(8)
	s_waitcnt lgkmcnt(0)
	s_barrier
	s_setprio 1
	s_waitcnt lgkmcnt(0)
	v_mfma_f32_16x16x32_bf16 v[60:63], v[128:131], v[182:185], v[60:63]
	v_mfma_f32_16x16x32_bf16 v[56:59], v[150:153], v[182:185], v[56:59]
	v_mfma_f32_16x16x32_bf16 v[44:47], v[128:131], v[190:193], v[44:47]
	v_mfma_f32_16x16x32_bf16 v[40:43], v[150:153], v[190:193], v[40:43]
	v_mfma_f32_16x16x32_bf16 v[28:31], v[128:131], v[198:201], v[28:31]
	v_mfma_f32_16x16x32_bf16 v[24:27], v[150:153], v[198:201], v[24:27]
	v_mfma_f32_16x16x32_bf16 v[12:15], v[128:131], v[206:209], v[12:15]
	v_mfma_f32_16x16x32_bf16 v[8:11], v[150:153], v[206:209], v[8:11]
	v_mfma_f32_16x16x32_bf16 v[60:63], v[132:135], v[186:189], v[60:63]
	v_mfma_f32_16x16x32_bf16 v[56:59], v[162:165], v[186:189], v[56:59]
	v_mfma_f32_16x16x32_bf16 v[44:47], v[132:135], v[194:197], v[44:47]
	v_mfma_f32_16x16x32_bf16 v[40:43], v[162:165], v[194:197], v[40:43]
	v_mfma_f32_16x16x32_bf16 v[28:31], v[132:135], v[202:205], v[28:31]
	v_mfma_f32_16x16x32_bf16 v[24:27], v[162:165], v[202:205], v[24:27]
	v_mfma_f32_16x16x32_bf16 v[12:15], v[132:135], v[214:217], v[12:15]
	v_mfma_f32_16x16x32_bf16 v[8:11], v[162:165], v[214:217], v[8:11]
	s_setprio 0
	s_setprio 1
	v_mfma_f32_16x16x32_bf16 v[52:55], v[166:169], v[182:185], v[52:55]
	v_mfma_f32_16x16x32_bf16 v[48:51], v[174:177], v[182:185], v[48:51]
	v_mfma_f32_16x16x32_bf16 v[36:39], v[166:169], v[190:193], v[36:39]
	v_mfma_f32_16x16x32_bf16 v[32:35], v[174:177], v[190:193], v[32:35]
	v_mfma_f32_16x16x32_bf16 v[20:23], v[166:169], v[198:201], v[20:23]
	v_mfma_f32_16x16x32_bf16 v[16:19], v[174:177], v[198:201], v[16:19]
	v_mfma_f32_16x16x32_bf16 v[4:7], v[166:169], v[206:209], v[4:7]
	v_mfma_f32_16x16x32_bf16 v[0:3], v[174:177], v[206:209], v[0:3]
	v_mfma_f32_16x16x32_bf16 v[52:55], v[170:173], v[186:189], v[52:55]
	v_mfma_f32_16x16x32_bf16 v[48:51], v[178:181], v[186:189], v[48:51]
	v_mfma_f32_16x16x32_bf16 v[36:39], v[170:173], v[194:197], v[36:39]
	v_mfma_f32_16x16x32_bf16 v[32:35], v[178:181], v[194:197], v[32:35]
	v_mfma_f32_16x16x32_bf16 v[20:23], v[170:173], v[202:205], v[20:23]
	v_mfma_f32_16x16x32_bf16 v[16:19], v[178:181], v[202:205], v[16:19]
	v_mfma_f32_16x16x32_bf16 v[4:7], v[170:173], v[214:217], v[4:7]
	v_mfma_f32_16x16x32_bf16 v[0:3], v[178:181], v[214:217], v[0:3]
	s_setprio 0
	s_barrier
	s_add_i32 s65, s65, 2
	s_add_u32 s55, s55, 0x100
	s_addc_u32 s64, s64, 0
	s_cmp_gt_u32 s65, 41
	s_mov_b64 s[24:25], s[26:27]
	s_cbranch_scc0 .LBB0_721
	v_lshl_add_u32 v152, s53, 8, v154
	v_ashrrev_i32_e32 v153, 31, v152
	s_lshl_b32 s16, s45, 8
	v_lshlrev_b64 v[128:129], 11, v[152:153]
	s_ashr_i32 s17, s16, 31
	v_lshl_add_u64 v[128:129], s[50:51], 0, v[128:129]
	v_lshl_add_u64 v[128:129], s[16:17], 1, v[128:129]
	v_lshl_add_u64 v[128:129], v[128:129], 0, s[14:15]
	v_lshl_add_u64 v[150:151], v[128:129], 0, v[144:145]
	s_mov_b32 s16, 0x8000
	v_add_co_u32_e32 v128, vcc, s16, v150
	global_load_dwordx4 v[164:167], v[150:151], off
	global_load_dwordx4 v[168:171], v[150:151], off offset:256
	v_addc_co_u32_e32 v129, vcc, 0, v151, vcc
	global_load_dwordx4 v[132:135], v[128:129], off
	s_nop 0
	global_load_dwordx4 v[128:131], v[128:129], off offset:256
	s_mov_b32 s100, 0x10000
	s_mov_b32 s101, 0
	v_lshl_add_u64 v[226:227], v[150:151], 0, s[100:101]
	global_load_dwordx4 v[228:231], v[226:227], off
	global_load_dwordx4 v[228:231], v[226:227], off offset:256
	s_mov_b32 s100, 0x18000
	s_mov_b32 s101, 0
	v_lshl_add_u64 v[226:227], v[150:151], 0, s[100:101]
	global_load_dwordx4 v[228:231], v[226:227], off
	global_load_dwordx4 v[228:231], v[226:227], off offset:256
	s_mov_b32 s100, 0x40000
	s_mov_b32 s101, 0
	v_lshl_add_u64 v[226:227], v[150:151], 0, s[100:101]
	global_load_dwordx4 v[228:231], v[226:227], off
	global_load_dwordx4 v[228:231], v[226:227], off offset:256
	s_mov_b32 s100, 0x48000
	s_mov_b32 s101, 0
	v_lshl_add_u64 v[226:227], v[150:151], 0, s[100:101]
	global_load_dwordx4 v[228:231], v[226:227], off
	global_load_dwordx4 v[228:231], v[226:227], off offset:256
	s_mov_b32 s100, 0x50000
	s_mov_b32 s101, 0
	v_lshl_add_u64 v[226:227], v[150:151], 0, s[100:101]
	global_load_dwordx4 v[228:231], v[226:227], off
	global_load_dwordx4 v[228:231], v[226:227], off offset:256
	s_mov_b32 s100, 0x58000
	s_mov_b32 s101, 0
	v_lshl_add_u64 v[226:227], v[150:151], 0, s[100:101]
	global_load_dwordx4 v[228:231], v[226:227], off
	global_load_dwordx4 v[228:231], v[226:227], off offset:256
	s_and_b64 vcc, exec, s[12:13]
	s_cbranch_vccz .LBB0_724
	s_barrier

; #define PG8_STAGE(bufoff, gbase, voff) do { _Pragma("unroll") for (int _i = 0; _i < 2; ++_i) \
;     __builtin_amdgcn_global_load_lds((const unsigned*)((const char*)(gbase) + (voff)[_i]), (PG8_LAS unsigned*)(lds + (bufoff) + ldsw + _i * 8192), 16, 0, 0); } while (0)
; #define PG8_LDA(dst, b, h) do { _Pragma("unroll") for (int m = 0; m < 4; ++m) _Pragma("unroll") for (int k = 0; k < 2; ++k) dst[m][k] = *(const PG8_LAS bf16x8*)(lds + PG8_SA(b, h) + aoff + m * 2048 + k * 1024); } while (0)
; #define PG8_LDB(dst, b, h) do { _Pragma("unroll") for (int n = 0; n < 2; ++n) _Pragma("unroll") for (int k = 0; k < 2; ++k) dst[n][k] = *(const PG8_LAS bf16x8*)(lds + PG8_SB(b, h) + boff + n * 2048 + k * 1024); } while (0)
; #define PG8_MMA(ai, bj, At, Bt) do { __builtin_amdgcn_s_setprio(1); _Pragma("unroll") for (int m = 0; m < 4; ++m) _Pragma("unroll") for (int n = 0; n < 2; ++n) _Pragma("unroll") for (int k = 0; k < 2; ++k) \
;     acc[ai][bj][m][n] = __builtin_amdgcn_mfma_f32_16x16x32_bf16(Bt[n][k], At[m][k], acc[ai][bj][m][n], 0, 0, 0); __builtin_amdgcn_s_setprio(0); } while (0)
; #define PG8_WAIT_V(n) asm volatile("s_waitcnt vmcnt(" #n ")" ::: "memory")
; #define PG8_WAIT_L(n) asm volatile("s_waitcnt lgkmcnt(" #n ")" ::: "memory")
; #define PG8_BAR __builtin_amdgcn_s_barrier()
; #define PG8_SCHED __builtin_amdgcn_sched_barrier(0)
; template <class Epi, class Sched>
; DI void gemm_phase(PG8_LAS unsigned char* lds, const Gemm g, const Sched& S, const Epi& E) {
;     ...
;       PG8_LDB(B0, 0, 0); PG8_LDB(B1, 0, 1); PG8_SCHED; PG8_LDA(At, 0, 0); PG8_STAGE(PG8_SA(1, 1), a1 + hstepA, voffA);
;       PG8_WAIT_V(8); PG8_WAIT_L(0); PG8_BAR; PG8_MMA(0, 0, At, B0); PG8_MMA(0, 1, At, B1); PG8_BAR; PG8_SCHED;
;       PG8_LDA(At, 0, 1); PG8_STAGE(PG8_SB(0, 0), b2, voffB); PG8_STAGE(PG8_SB(0, 1), b2 + hstepB, voffB); PG8_STAGE(PG8_SA(0, 0), a2, voffA);
;       PG8_WAIT_V(8); PG8_WAIT_L(0); PG8_BAR; PG8_MMA(1, 0, At, B0); PG8_MMA(1, 1, At, B1); PG8_BAR; PG8_SCHED;
.LBB0_1300:
	ds_read_b128 v[128:131], v156
	ds_read_b128 v[132:135], v156 offset:1024
	ds_read_b128 v[150:153], v156 offset:2048
	ds_read_b128 v[162:165], v156 offset:3072
	ds_read_b128 v[166:169], v157
	ds_read_b128 v[170:173], v157 offset:1024
	ds_read_b128 v[174:177], v157 offset:2048
	ds_read_b128 v[178:181], v157 offset:3072
	s_add_u32 s17, s62, 0xfffc0080
	s_addc_u32 s33, s63, -1
	s_cmp_eq_u32 s75, 12
	s_cselect_b32 s67, s39, s33
	s_cselect_b32 s66, s59, s17
	s_cselect_b32 s65, s37, s74
	s_cselect_b32 s64, s61, s73
	v_lshl_add_u64 v[210:211], s[62:63], 0, v[146:147]
	s_add_i32 m0, s53, 0xc000
	ds_read_b128 v[182:185], v158
	ds_read_b128 v[186:189], v158 offset:1024
	ds_read_b128 v[190:193], v158 offset:2048
	ds_read_b128 v[194:197], v158 offset:3072
	ds_read_b128 v[198:201], v158 offset:4096
	ds_read_b128 v[202:205], v158 offset:5120
	ds_read_b128 v[206:209], v158 offset:6144
	ds_read_b128 v[214:217], v158 offset:7168
	global_load_lds_dwordx4 v[210:211], off
	v_lshl_add_u64 v[210:211], s[62:63], 0, v[148:149]
	s_add_i32 m0, s53, 0xe000
	s_nop 0
	global_load_lds_dwordx4 v[210:211], off
	s_waitcnt vmcnt(8)
	s_waitcnt lgkmcnt(0)
	s_barrier
	s_setprio 1
	s_waitcnt lgkmcnt(0)
	v_mfma_f32_16x16x32_bf16 v[124:127], v[128:131], v[182:185], v[124:127]
	v_mfma_f32_16x16x32_bf16 v[120:123], v[150:153], v[182:185], v[120:123]
	v_mfma_f32_16x16x32_bf16 v[108:111], v[128:131], v[190:193], v[108:111]
	v_mfma_f32_16x16x32_bf16 v[104:107], v[150:153], v[190:193], v[104:107]
	v_mfma_f32_16x16x32_bf16 v[92:95], v[128:131], v[198:201], v[92:95]
	v_mfma_f32_16x16x32_bf16 v[88:91], v[150:153], v[198:201], v[88:91]
	v_mfma_f32_16x16x32_bf16 v[76:79], v[128:131], v[206:209], v[76:79]
	v_mfma_f32_16x16x32_bf16 v[72:75], v[150:153], v[206:209], v[72:75]
	v_mfma_f32_16x16x32_bf16 v[124:127], v[132:135], v[186:189], v[124:127]
	v_mfma_f32_16x16x32_bf16 v[120:123], v[162:165], v[186:189], v[120:123]
	v_mfma_f32_16x16x32_bf16 v[108:111], v[132:135], v[194:197], v[108:111]
	v_mfma_f32_16x16x32_bf16 v[104:107], v[162:165], v[194:197], v[104:107]
	v_mfma_f32_16x16x32_bf16 v[92:95], v[132:135], v[202:205], v[92:95]
	v_mfma_f32_16x16x32_bf16 v[88:91], v[162:165], v[202:205], v[88:91]
	v_mfma_f32_16x16x32_bf16 v[76:79], v[132:135], v[214:217], v[76:79]
	v_mfma_f32_16x16x32_bf16 v[72:75], v[162:165], v[214:217], v[72:75]
	s_setprio 0
	s_setprio 1
	v_mfma_f32_16x16x32_bf16 v[116:119], v[166:169], v[182:185], v[116:119]
	v_mfma_f32_16x16x32_bf16 v[112:115], v[174:177], v[182:185], v[112:115]
	v_mfma_f32_16x16x32_bf16 v[100:103], v[166:169], v[190:193], v[100:103]
	v_mfma_f32_16x16x32_bf16 v[96:99], v[174:177], v[190:193], v[96:99]
	v_mfma_f32_16x16x32_bf16 v[84:87], v[166:169], v[198:201], v[84:87]
	v_mfma_f32_16x16x32_bf16 v[80:83], v[174:177], v[198:201], v[80:83]
	v_mfma_f32_16x16x32_bf16 v[68:71], v[166:169], v[206:209], v[68:71]
	v_mfma_f32_16x16x32_bf16 v[64:67], v[174:177], v[206:209], v[64:67]
	v_mfma_f32_16x16x32_bf16 v[116:119], v[170:173], v[186:189], v[116:119]
	v_mfma_f32_16x16x32_bf16 v[112:115], v[178:181], v[186:189], v[112:115]
	v_mfma_f32_16x16x32_bf16 v[100:103], v[170:173], v[194:197], v[100:103]
	v_mfma_f32_16x16x32_bf16 v[96:99], v[178:181], v[194:197], v[96:99]
	v_mfma_f32_16x16x32_bf16 v[84:87], v[170:173], v[202:205], v[84:87]
	v_mfma_f32_16x16x32_bf16 v[80:83], v[178:181], v[202:205], v[80:83]
	v_mfma_f32_16x16x32_bf16 v[68:71], v[170:173], v[214:217], v[68:71]
	v_mfma_f32_16x16x32_bf16 v[64:67], v[178:181], v[214:217], v[64:67]
	s_setprio 0
	s_barrier
	s_add_i32 s17, s69, s16
	v_lshl_add_u64 v[210:211], s[64:65], 0, v[138:139]
	s_mov_b32 m0, s17
	ds_read_b128 v[182:185], v158 offset:16384
	ds_read_b128 v[186:189], v158 offset:17408
	ds_read_b128 v[190:193], v158 offset:18432
	ds_read_b128 v[194:197], v158 offset:19456
	ds_read_b128 v[198:201], v158 offset:20480
	ds_read_b128 v[202:205], v158 offset:21504
	ds_read_b128 v[206:209], v158 offset:22528
	ds_read_b128 v[214:217], v158 offset:23552
	global_load_lds_dwordx4 v[210:211], off
	s_add_i32 m0, s17, 0x2000
	s_add_u32 s56, s64, 0x40000
	v_lshl_add_u64 v[218:219], s[64:65], 0, v[142:143]
	s_addc_u32 s57, s65, 0
	s_add_i32 s17, s70, s16
	global_load_lds_dwordx4 v[218:219], off
	v_lshl_add_u64 v[220:221], s[56:57], 0, v[138:139]
	s_mov_b32 m0, s17
	v_lshl_add_u64 v[222:223], s[66:67], 0, v[140:141]
	global_load_lds_dwordx4 v[220:221], off
	v_lshl_add_u64 v[220:221], s[56:57], 0, v[142:143]
	s_add_i32 m0, s17, 0x2000
	s_nop 0
	global_load_lds_dwordx4 v[220:221], off
	v_lshl_add_u64 v[220:221], s[66:67], 0, v[136:137]
	s_mov_b32 m0, s53
	s_nop 0
	global_load_lds_dwordx4 v[220:221], off
	s_mov_b32 m0, s18
	s_nop 0
	global_load_lds_dwordx4 v[222:223], off
	s_waitcnt vmcnt(8)
	s_waitcnt lgkmcnt(0)
	s_barrier
; #define PG8_STAGE(bufoff, gbase, voff) do { _Pragma("unroll") for (int _i = 0; _i < 2; ++_i) \
;     __builtin_amdgcn_global_load_lds((const unsigned*)((const char*)(gbase) + (voff)[_i]), (PG8_LAS unsigned*)(lds + (bufoff) + ldsw + _i * 8192), 16, 0, 0); } while (0)
; #define PG8_LDA(dst, b, h) do { _Pragma("unroll") for (int m = 0; m < 4; ++m) _Pragma("unroll") for (int k = 0; k < 2; ++k) dst[m][k] = *(const PG8_LAS bf16x8*)(lds + PG8_SA(b, h) + aoff + m * 2048 + k * 1024); } while (0)
; #define PG8_LDB(dst, b, h) do { _Pragma("unroll") for (int n = 0; n < 2; ++n) _Pragma("unroll") for (int k = 0; k < 2; ++k) dst[n][k] = *(const PG8_LAS bf16x8*)(lds + PG8_SB(b, h) + boff + n * 2048 + k * 1024); } while (0)
; #define PG8_MMA(ai, bj, At, Bt) do { __builtin_amdgcn_s_setprio(1); _Pragma("unroll") for (int m = 0; m < 4; ++m) _Pragma("unroll") for (int n = 0; n < 2; ++n) _Pragma("unroll") for (int k = 0; k < 2; ++k) \
;     acc[ai][bj][m][n] = __builtin_amdgcn_mfma_f32_16x16x32_bf16(Bt[n][k], At[m][k], acc[ai][bj][m][n], 0, 0, 0); __builtin_amdgcn_s_setprio(0); } while (0)
; #define PG8_WAIT_V(n) asm volatile("s_waitcnt vmcnt(" #n ")" ::: "memory")
; #define PG8_WAIT_L(n) asm volatile("s_waitcnt lgkmcnt(" #n ")" ::: "memory")
; #define PG8_BAR __builtin_amdgcn_s_barrier()
; #define PG8_SCHED __builtin_amdgcn_sched_barrier(0)
; template <class Epi, class Sched>
; DI void gemm_phase(PG8_LAS unsigned char* lds, const Gemm g, const Sched& S, const Epi& E) {
;     ...
;       PG8_WAIT_V(8); PG8_WAIT_L(0); PG8_BAR; PG8_MMA(1, 0, At, B0); PG8_MMA(1, 1, At, B1); PG8_BAR; PG8_SCHED;
;       PG8_LDB(B0, 1, 0); PG8_LDB(B1, 1, 1); PG8_SCHED; PG8_LDA(At, 1, 0); PG8_STAGE(PG8_SA(0, 1), a2 + hstepA, voffA);
;       PG8_WAIT_V(8); PG8_WAIT_L(0); PG8_BAR; PG8_MMA(0, 0, At, B0); PG8_MMA(0, 1, At, B1); PG8_BAR; PG8_SCHED;
;       PG8_LDA(At, 1, 1); PG8_STAGE(PG8_SB(1, 0), b3, voffB); PG8_STAGE(PG8_SB(1, 1), b3 + hstepB, voffB); PG8_STAGE(PG8_SA(1, 0), a3, voffA);
;       PG8_WAIT_V(8); PG8_WAIT_L(0); PG8_BAR; PG8_MMA(1, 0, At, B0); PG8_MMA(1, 1, At, B1); PG8_BAR; PG8_SCHED;
	s_setprio 1
	s_waitcnt lgkmcnt(0)
	v_mfma_f32_16x16x32_bf16 v[60:63], v[128:131], v[182:185], v[60:63]
	v_mfma_f32_16x16x32_bf16 v[56:59], v[150:153], v[182:185], v[56:59]
	v_mfma_f32_16x16x32_bf16 v[44:47], v[128:131], v[190:193], v[44:47]
	v_mfma_f32_16x16x32_bf16 v[40:43], v[150:153], v[190:193], v[40:43]
	v_mfma_f32_16x16x32_bf16 v[28:31], v[128:131], v[198:201], v[28:31]
	v_mfma_f32_16x16x32_bf16 v[24:27], v[150:153], v[198:201], v[24:27]
	v_mfma_f32_16x16x32_bf16 v[12:15], v[128:131], v[206:209], v[12:15]
	v_mfma_f32_16x16x32_bf16 v[8:11], v[150:153], v[206:209], v[8:11]
	v_mfma_f32_16x16x32_bf16 v[60:63], v[132:135], v[186:189], v[60:63]
	v_mfma_f32_16x16x32_bf16 v[56:59], v[162:165], v[186:189], v[56:59]
	v_mfma_f32_16x16x32_bf16 v[44:47], v[132:135], v[194:197], v[44:47]
	v_mfma_f32_16x16x32_bf16 v[40:43], v[162:165], v[194:197], v[40:43]
	v_mfma_f32_16x16x32_bf16 v[28:31], v[132:135], v[202:205], v[28:31]
	v_mfma_f32_16x16x32_bf16 v[24:27], v[162:165], v[202:205], v[24:27]
	v_mfma_f32_16x16x32_bf16 v[12:15], v[132:135], v[214:217], v[12:15]
	v_mfma_f32_16x16x32_bf16 v[8:11], v[162:165], v[214:217], v[8:11]
	s_setprio 0
	s_setprio 1
	v_mfma_f32_16x16x32_bf16 v[52:55], v[166:169], v[182:185], v[52:55]
	v_mfma_f32_16x16x32_bf16 v[48:51], v[174:177], v[182:185], v[48:51]
	v_mfma_f32_16x16x32_bf16 v[36:39], v[166:169], v[190:193], v[36:39]
	v_mfma_f32_16x16x32_bf16 v[32:35], v[174:177], v[190:193], v[32:35]
	v_mfma_f32_16x16x32_bf16 v[20:23], v[166:169], v[198:201], v[20:23]
	v_mfma_f32_16x16x32_bf16 v[16:19], v[174:177], v[198:201], v[16:19]
	v_mfma_f32_16x16x32_bf16 v[4:7], v[166:169], v[206:209], v[4:7]
	v_mfma_f32_16x16x32_bf16 v[0:3], v[174:177], v[206:209], v[0:3]
	v_mfma_f32_16x16x32_bf16 v[52:55], v[170:173], v[186:189], v[52:55]
	v_mfma_f32_16x16x32_bf16 v[48:51], v[178:181], v[186:189], v[48:51]
	v_mfma_f32_16x16x32_bf16 v[36:39], v[170:173], v[194:197], v[36:39]
	v_mfma_f32_16x16x32_bf16 v[32:35], v[178:181], v[194:197], v[32:35]
	v_mfma_f32_16x16x32_bf16 v[20:23], v[170:173], v[202:205], v[20:23]
	v_mfma_f32_16x16x32_bf16 v[16:19], v[178:181], v[202:205], v[16:19]
	v_mfma_f32_16x16x32_bf16 v[4:7], v[170:173], v[214:217], v[4:7]
	v_mfma_f32_16x16x32_bf16 v[0:3], v[178:181], v[214:217], v[0:3]
	s_setprio 0
	s_barrier
	s_mov_b32 s17, 0x18000
	s_addk_i32 s17, 0x110
	v_add_u32_e32 v161, s17, v155
	ds_read_b128 v[128:131], v161
	ds_read_b128 v[132:135], v161 offset:1024
	ds_read_b128 v[150:153], v161 offset:2048
	ds_read_b128 v[162:165], v161 offset:3072
	ds_read_b128 v[166:169], v160
	ds_read_b128 v[170:173], v160 offset:1024
	ds_read_b128 v[174:177], v160 offset:2048
	ds_read_b128 v[178:181], v160 offset:3072
	s_add_u32 s56, s66, 0x40000
	s_addc_u32 s57, s67, 0
	s_mov_b32 m0, s19
	v_lshl_add_u64 v[224:225], s[56:57], 0, v[136:137]
	ds_read_b128 v[182:185], v158 offset:32768
	ds_read_b128 v[186:189], v158 offset:33792
	ds_read_b128 v[190:193], v158 offset:34816
	ds_read_b128 v[194:197], v158 offset:35840
	ds_read_b128 v[198:201], v158 offset:36864
	ds_read_b128 v[202:205], v158 offset:37888
	ds_read_b128 v[206:209], v158 offset:38912
	ds_read_b128 v[214:217], v158 offset:39936
	global_load_lds_dwordx4 v[224:225], off
	v_lshl_add_u64 v[224:225], s[56:57], 0, v[140:141]
	s_mov_b32 m0, s54
	s_nop 0
	global_load_lds_dwordx4 v[224:225], off
	s_waitcnt vmcnt(8)
	s_waitcnt lgkmcnt(0)
	s_barrier
	s_setprio 1
	s_waitcnt lgkmcnt(0)
	v_mfma_f32_16x16x32_bf16 v[124:127], v[128:131], v[182:185], v[124:127]
	v_mfma_f32_16x16x32_bf16 v[120:123], v[150:153], v[182:185], v[120:123]
	v_mfma_f32_16x16x32_bf16 v[108:111], v[128:131], v[190:193], v[108:111]
	v_mfma_f32_16x16x32_bf16 v[104:107], v[150:153], v[190:193], v[104:107]
	v_mfma_f32_16x16x32_bf16 v[92:95], v[128:131], v[198:201], v[92:95]
	v_mfma_f32_16x16x32_bf16 v[88:91], v[150:153], v[198:201], v[88:91]
	v_mfma_f32_16x16x32_bf16 v[76:79], v[128:131], v[206:209], v[76:79]
	v_mfma_f32_16x16x32_bf16 v[72:75], v[150:153], v[206:209], v[72:75]
	v_mfma_f32_16x16x32_bf16 v[124:127], v[132:135], v[186:189], v[124:127]
	v_mfma_f32_16x16x32_bf16 v[120:123], v[162:165], v[186:189], v[120:123]
	v_mfma_f32_16x16x32_bf16 v[108:111], v[132:135], v[194:197], v[108:111]
	v_mfma_f32_16x16x32_bf16 v[104:107], v[162:165], v[194:197], v[104:107]
	v_mfma_f32_16x16x32_bf16 v[92:95], v[132:135], v[202:205], v[92:95]
	v_mfma_f32_16x16x32_bf16 v[88:91], v[162:165], v[202:205], v[88:91]
	v_mfma_f32_16x16x32_bf16 v[76:79], v[132:135], v[214:217], v[76:79]
	v_mfma_f32_16x16x32_bf16 v[72:75], v[162:165], v[214:217], v[72:75]
	s_setprio 0
	s_setprio 1
	v_mfma_f32_16x16x32_bf16 v[116:119], v[166:169], v[182:185], v[116:119]
	v_mfma_f32_16x16x32_bf16 v[112:115], v[174:177], v[182:185], v[112:115]
	v_mfma_f32_16x16x32_bf16 v[100:103], v[166:169], v[190:193], v[100:103]
	v_mfma_f32_16x16x32_bf16 v[96:99], v[174:177], v[190:193], v[96:99]
	v_mfma_f32_16x16x32_bf16 v[84:87], v[166:169], v[198:201], v[84:87]
	v_mfma_f32_16x16x32_bf16 v[80:83], v[174:177], v[198:201], v[80:83]
	v_mfma_f32_16x16x32_bf16 v[68:71], v[166:169], v[206:209], v[68:71]
	v_mfma_f32_16x16x32_bf16 v[64:67], v[174:177], v[206:209], v[64:67]
	v_mfma_f32_16x16x32_bf16 v[116:119], v[170:173], v[186:189], v[116:119]
	v_mfma_f32_16x16x32_bf16 v[112:115], v[178:181], v[186:189], v[112:115]
	v_mfma_f32_16x16x32_bf16 v[100:103], v[170:173], v[194:197], v[100:103]
	v_mfma_f32_16x16x32_bf16 v[96:99], v[178:181], v[194:197], v[96:99]
	v_mfma_f32_16x16x32_bf16 v[84:87], v[170:173], v[202:205], v[84:87]
	v_mfma_f32_16x16x32_bf16 v[80:83], v[178:181], v[202:205], v[80:83]
	v_mfma_f32_16x16x32_bf16 v[68:71], v[170:173], v[214:217], v[68:71]
	v_mfma_f32_16x16x32_bf16 v[64:67], v[178:181], v[214:217], v[64:67]
	s_setprio 0
	s_barrier
; #define PG8_STAGE(bufoff, gbase, voff) do { _Pragma("unroll") for (int _i = 0; _i < 2; ++_i) \
;     __builtin_amdgcn_global_load_lds((const unsigned*)((const char*)(gbase) + (voff)[_i]), (PG8_LAS unsigned*)(lds + (bufoff) + ldsw + _i * 8192), 16, 0, 0); } while (0)
; #define PG8_LDA(dst, b, h) do { _Pragma("unroll") for (int m = 0; m < 4; ++m) _Pragma("unroll") for (int k = 0; k < 2; ++k) dst[m][k] = *(const PG8_LAS bf16x8*)(lds + PG8_SA(b, h) + aoff + m * 2048 + k * 1024); } while (0)
; #define PG8_MMA(ai, bj, At, Bt) do { __builtin_amdgcn_s_setprio(1); _Pragma("unroll") for (int m = 0; m < 4; ++m) _Pragma("unroll") for (int n = 0; n < 2; ++n) _Pragma("unroll") for (int k = 0; k < 2; ++k) \
;     acc[ai][bj][m][n] = __builtin_amdgcn_mfma_f32_16x16x32_bf16(Bt[n][k], At[m][k], acc[ai][bj][m][n], 0, 0, 0); __builtin_amdgcn_s_setprio(0); } while (0)
; #define PG8_WAIT_V(n) asm volatile("s_waitcnt vmcnt(" #n ")" ::: "memory")
; #define PG8_WAIT_L(n) asm volatile("s_waitcnt lgkmcnt(" #n ")" ::: "memory")
; #define PG8_BAR __builtin_amdgcn_s_barrier()
; #define PG8_SCHED __builtin_amdgcn_sched_barrier(0)
;   DI void operator()(const f32x4 (&acc)[2][2][4][2], const Unit& u, int wr, int wc, int fr, int fq) const {
;     const int row0 = u.pm * BM + wr * 64 + fr;
;     const size_t base = (size_t)row0 * DM + u.pn * BM + wc * 32 + 8 * fq;
;     f32x4 xv[2][4];
;     u32x4 xh[2][2];
;     ...
;     RES_LD(0)
; #pragma unroll
;     for (int i = 0; i < 8; ++i) {
;       const int ai = i >> 2, m = i & 3;
;       if (i + 1 < 8) RES_LD(i + 1)
; template <class Epi, class Sched>
; DI void gemm_phase(PG8_LAS unsigned char* lds, const Gemm g, const Sched& S, const Epi& E) {
;     ...
;       PG8_LDA(At, 1, 1); PG8_STAGE(PG8_SB(1, 0), b3, voffB); PG8_STAGE(PG8_SB(1, 1), b3 + hstepB, voffB); PG8_STAGE(PG8_SA(1, 0), a3, voffA);
;       PG8_WAIT_V(8); PG8_WAIT_L(0); PG8_BAR; PG8_MMA(1, 0, At, B0); PG8_MMA(1, 1, At, B1); PG8_BAR; PG8_SCHED;
;     }
	s_add_i32 s17, s17, s16
	v_lshl_add_u64 v[210:211], v[210:211], 0, s[6:7]
	s_mov_b32 m0, s17
	ds_read_b128 v[182:185], v158 offset:49152
	ds_read_b128 v[186:189], v158 offset:50176
	ds_read_b128 v[190:193], v158 offset:51200
	ds_read_b128 v[194:197], v158 offset:52224
	ds_read_b128 v[198:201], v158 offset:53248
	ds_read_b128 v[202:205], v158 offset:54272
	ds_read_b128 v[206:209], v158 offset:55296
	ds_read_b128 v[214:217], v158 offset:56320
	global_load_lds_dwordx4 v[210:211], off
	s_add_i32 m0, s17, 0x2000
	s_add_u32 s56, s64, 0x40080
	v_lshl_add_u64 v[210:211], v[218:219], 0, s[6:7]
	s_addc_u32 s57, s65, 0
	s_add_i32 s17, s71, s16
	global_load_lds_dwordx4 v[210:211], off
	v_lshl_add_u64 v[210:211], s[56:57], 0, v[138:139]
	s_mov_b32 m0, s17
	s_nop 0
	global_load_lds_dwordx4 v[210:211], off
	v_lshl_add_u64 v[210:211], s[56:57], 0, v[142:143]
	s_add_i32 m0, s17, 0x2000
	s_nop 0
	global_load_lds_dwordx4 v[210:211], off
	v_lshl_add_u64 v[210:211], v[220:221], 0, s[6:7]
	s_mov_b32 m0, s5
	s_nop 0
	global_load_lds_dwordx4 v[210:211], off
	v_lshl_add_u64 v[210:211], v[222:223], 0, s[6:7]
	s_mov_b32 m0, s55
	s_nop 0
	global_load_lds_dwordx4 v[210:211], off
	s_waitcnt vmcnt(8)
	s_waitcnt lgkmcnt(0)
	s_barrier
	s_setprio 1
	s_waitcnt lgkmcnt(0)
	v_mfma_f32_16x16x32_bf16 v[60:63], v[128:131], v[182:185], v[60:63]
	v_mfma_f32_16x16x32_bf16 v[56:59], v[150:153], v[182:185], v[56:59]
	v_mfma_f32_16x16x32_bf16 v[44:47], v[128:131], v[190:193], v[44:47]
	v_mfma_f32_16x16x32_bf16 v[40:43], v[150:153], v[190:193], v[40:43]
	v_mfma_f32_16x16x32_bf16 v[28:31], v[128:131], v[198:201], v[28:31]
	v_mfma_f32_16x16x32_bf16 v[24:27], v[150:153], v[198:201], v[24:27]
	v_mfma_f32_16x16x32_bf16 v[12:15], v[128:131], v[206:209], v[12:15]
	v_mfma_f32_16x16x32_bf16 v[8:11], v[150:153], v[206:209], v[8:11]
	v_mfma_f32_16x16x32_bf16 v[60:63], v[132:135], v[186:189], v[60:63]
	v_mfma_f32_16x16x32_bf16 v[56:59], v[162:165], v[186:189], v[56:59]
	v_mfma_f32_16x16x32_bf16 v[44:47], v[132:135], v[194:197], v[44:47]
	v_mfma_f32_16x16x32_bf16 v[40:43], v[162:165], v[194:197], v[40:43]
	v_mfma_f32_16x16x32_bf16 v[28:31], v[132:135], v[202:205], v[28:31]
	v_mfma_f32_16x16x32_bf16 v[24:27], v[162:165], v[202:205], v[24:27]
	v_mfma_f32_16x16x32_bf16 v[12:15], v[132:135], v[214:217], v[12:15]
	v_mfma_f32_16x16x32_bf16 v[8:11], v[162:165], v[214:217], v[8:11]
	s_setprio 0
	s_setprio 1
	v_mfma_f32_16x16x32_bf16 v[52:55], v[166:169], v[182:185], v[52:55]
	v_mfma_f32_16x16x32_bf16 v[48:51], v[174:177], v[182:185], v[48:51]
	v_mfma_f32_16x16x32_bf16 v[36:39], v[166:169], v[190:193], v[36:39]
	v_mfma_f32_16x16x32_bf16 v[32:35], v[174:177], v[190:193], v[32:35]
	v_mfma_f32_16x16x32_bf16 v[20:23], v[166:169], v[198:201], v[20:23]
	v_mfma_f32_16x16x32_bf16 v[16:19], v[174:177], v[198:201], v[16:19]
	v_mfma_f32_16x16x32_bf16 v[4:7], v[166:169], v[206:209], v[4:7]
	v_mfma_f32_16x16x32_bf16 v[0:3], v[174:177], v[206:209], v[0:3]
	v_mfma_f32_16x16x32_bf16 v[52:55], v[170:173], v[186:189], v[52:55]
	v_mfma_f32_16x16x32_bf16 v[48:51], v[178:181], v[186:189], v[48:51]
	v_mfma_f32_16x16x32_bf16 v[36:39], v[170:173], v[194:197], v[36:39]
	v_mfma_f32_16x16x32_bf16 v[32:35], v[178:181], v[194:197], v[32:35]
	v_mfma_f32_16x16x32_bf16 v[20:23], v[170:173], v[202:205], v[20:23]
	v_mfma_f32_16x16x32_bf16 v[16:19], v[178:181], v[202:205], v[16:19]
	v_mfma_f32_16x16x32_bf16 v[4:7], v[170:173], v[214:217], v[4:7]
	v_mfma_f32_16x16x32_bf16 v[0:3], v[178:181], v[214:217], v[0:3]
	s_setprio 0
	s_barrier
	s_add_i32 s75, s75, 2
	s_add_u32 s62, s62, 0x100
	s_addc_u32 s63, s63, 0
	s_add_u32 s73, s73, 0x100
	s_addc_u32 s74, s74, 0
	s_cmp_gt_u32 s75, 13
	s_cbranch_scc0 .LBB0_1300
	v_lshl_add_u32 v152, s60, 8, v154
	v_ashrrev_i32_e32 v153, 31, v152
	s_lshl_b32 s56, s58, 8
	v_lshlrev_b64 v[128:129], 11, v[152:153]
	s_ashr_i32 s57, s56, 31
	v_lshl_add_u64 v[128:129], s[50:51], 0, v[128:129]
	v_lshl_add_u64 v[128:129], s[56:57], 1, v[128:129]
	v_lshl_add_u64 v[128:129], v[128:129], 0, s[10:11]
	v_lshl_add_u64 v[150:151], v[128:129], 0, v[144:145]
	s_mov_b32 s17, 0x8000
	v_add_co_u32_e32 v128, vcc, s17, v150
	global_load_dwordx4 v[164:167], v[150:151], off
	global_load_dwordx4 v[168:171], v[150:151], off offset:256
	v_addc_co_u32_e32 v129, vcc, 0, v151, vcc
	global_load_dwordx4 v[132:135], v[128:129], off
	s_nop 0
	global_load_dwordx4 v[128:131], v[128:129], off offset:256
	s_mov_b32 s100, 0x10000
	s_mov_b32 s101, 0
	v_lshl_add_u64 v[226:227], v[150:151], 0, s[100:101]
	global_load_dwordx4 v[228:231], v[226:227], off
	global_load_dwordx4 v[228:231], v[226:227], off offset:256
	s_mov_b32 s100, 0x18000
	s_mov_b32 s101, 0
	v_lshl_add_u64 v[226:227], v[150:151], 0, s[100:101]
	global_load_dwordx4 v[228:231], v[226:227], off
	global_load_dwordx4 v[228:231], v[226:227], off offset:256
	s_mov_b32 s100, 0x40000
	s_mov_b32 s101, 0
	v_lshl_add_u64 v[226:227], v[150:151], 0, s[100:101]
	global_load_dwordx4 v[228:231], v[226:227], off
	global_load_dwordx4 v[228:231], v[226:227], off offset:256
	s_mov_b32 s100, 0x48000
	s_mov_b32 s101, 0
	v_lshl_add_u64 v[226:227], v[150:151], 0, s[100:101]
	global_load_dwordx4 v[228:231], v[226:227], off
	global_load_dwordx4 v[228:231], v[226:227], off offset:256
	s_mov_b32 s100, 0x50000
	s_mov_b32 s101, 0
	v_lshl_add_u64 v[226:227], v[150:151], 0, s[100:101]
	global_load_dwordx4 v[228:231], v[226:227], off
	global_load_dwordx4 v[228:231], v[226:227], off offset:256
	s_mov_b32 s100, 0x58000
	s_mov_b32 s101, 0
	v_lshl_add_u64 v[226:227], v[150:151], 0, s[100:101]
	global_load_dwordx4 v[228:231], v[226:227], off
	global_load_dwordx4 v[228:231], v[226:227], off offset:256
	s_and_b64 vcc, exec, s[8:9]
	s_cbranch_vccz .LBB0_1303
	s_barrier

; #define PG8_STAGE(bufoff, gbase, voff) do { _Pragma("unroll") for (int _i = 0; _i < 2; ++_i) \
;     __builtin_amdgcn_global_load_lds((const unsigned*)((const char*)(gbase) + (voff)[_i]), (PG8_LAS unsigned*)(lds + (bufoff) + ldsw + _i * 8192), 16, 0, 0); } while (0)
; #define PG8_LDA(dst, b, h) do { _Pragma("unroll") for (int m = 0; m < 4; ++m) _Pragma("unroll") for (int k = 0; k < 2; ++k) dst[m][k] = *(const PG8_LAS bf16x8*)(lds + PG8_SA(b, h) + aoff + m * 2048 + k * 1024); } while (0)
; #define PG8_LDB(dst, b, h) do { _Pragma("unroll") for (int n = 0; n < 2; ++n) _Pragma("unroll") for (int k = 0; k < 2; ++k) dst[n][k] = *(const PG8_LAS bf16x8*)(lds + PG8_SB(b, h) + boff + n * 2048 + k * 1024); } while (0)
; #define PG8_MMA(ai, bj, At, Bt) do { __builtin_amdgcn_s_setprio(1); _Pragma("unroll") for (int m = 0; m < 4; ++m) _Pragma("unroll") for (int n = 0; n < 2; ++n) _Pragma("unroll") for (int k = 0; k < 2; ++k) \
;     acc[ai][bj][m][n] = __builtin_amdgcn_mfma_f32_16x16x32_bf16(Bt[n][k], At[m][k], acc[ai][bj][m][n], 0, 0, 0); __builtin_amdgcn_s_setprio(0); } while (0)
; #define PG8_WAIT_V(n) asm volatile("s_waitcnt vmcnt(" #n ")" ::: "memory")
; #define PG8_WAIT_L(n) asm volatile("s_waitcnt lgkmcnt(" #n ")" ::: "memory")
; #define PG8_BAR __builtin_amdgcn_s_barrier()
; #define PG8_SCHED __builtin_amdgcn_sched_barrier(0)
; template <class Epi, class Sched>
; DI void gemm_phase(PG8_LAS unsigned char* lds, const Gemm g, const Sched& S, const Epi& E) {
;     ...
;       const char* a1 = cA + (size_t)(t + 1) * kstep;
;       const char* a2 = last ? nA : cA + (size_t)(t + 2) * kstep; const char* b2 = last ? nB : cB + (size_t)(t + 2) * kstep;
;       const char* a3 = a2 + kstep; const char* b3 = b2 + kstep;
;       PG8_LDB(B0, 0, 0); PG8_LDB(B1, 0, 1); PG8_SCHED; PG8_LDA(At, 0, 0); PG8_STAGE(PG8_SA(1, 1), a1 + hstepA, voffA);
;       PG8_WAIT_V(8); PG8_WAIT_L(0); PG8_BAR; PG8_MMA(0, 0, At, B0); PG8_MMA(0, 1, At, B1); PG8_BAR; PG8_SCHED;
;       PG8_LDA(At, 0, 1); PG8_STAGE(PG8_SB(0, 0), b2, voffB); PG8_STAGE(PG8_SB(0, 1), b2 + hstepB, voffB); PG8_STAGE(PG8_SA(0, 0), a2, voffA);
;       PG8_WAIT_V(8); PG8_WAIT_L(0); PG8_BAR; PG8_MMA(1, 0, At, B0); PG8_MMA(1, 1, At, B1); PG8_BAR; PG8_SCHED;
.LBB0_1456:
	ds_read_b128 v[150:153], v145
	ds_read_b128 v[154:157], v145 offset:1024
	ds_read_b128 v[158:161], v145 offset:2048
	ds_read_b128 v[162:165], v145 offset:3072
	ds_read_b128 v[166:169], v146
	ds_read_b128 v[170:173], v146 offset:1024
	ds_read_b128 v[174:177], v146 offset:2048
	ds_read_b128 v[178:181], v146 offset:3072
	s_add_u32 s14, s12, 0x100
	s_addc_u32 s15, s13, 0
	s_cmp_eq_u32 s60, 40
	s_cselect_b32 s19, s9, s15
	s_cselect_b32 s18, s8, s14
	s_cselect_b32 s17, s11, s59
	s_cselect_b32 s16, s10, s58
	s_mov_b32 m0, s49
	v_lshl_add_u64 v[142:143], s[12:13], 0, v[138:139]
	ds_read_b128 v[182:185], v147
	ds_read_b128 v[186:189], v147 offset:1024
	ds_read_b128 v[190:193], v147 offset:2048
	ds_read_b128 v[194:197], v147 offset:3072
	ds_read_b128 v[198:201], v147 offset:4096
	ds_read_b128 v[202:205], v147 offset:5120
	ds_read_b128 v[206:209], v147 offset:6144
	ds_read_b128 v[210:213], v147 offset:7168
	global_load_lds_dwordx4 v[142:143], off
	v_lshl_add_u64 v[142:143], s[12:13], 0, v[140:141]
	s_mov_b32 m0, s52
	s_nop 0
	global_load_lds_dwordx4 v[142:143], off
	s_waitcnt vmcnt(8)
	s_waitcnt lgkmcnt(0)
	s_barrier
	s_setprio 1
	s_waitcnt lgkmcnt(0)
	v_mfma_f32_16x16x32_bf16 v[124:127], v[150:153], v[182:185], v[124:127]
	v_mfma_f32_16x16x32_bf16 v[120:123], v[158:161], v[182:185], v[120:123]
	v_mfma_f32_16x16x32_bf16 v[108:111], v[150:153], v[190:193], v[108:111]
	v_mfma_f32_16x16x32_bf16 v[104:107], v[158:161], v[190:193], v[104:107]
	v_mfma_f32_16x16x32_bf16 v[92:95], v[150:153], v[198:201], v[92:95]
	v_mfma_f32_16x16x32_bf16 v[88:91], v[158:161], v[198:201], v[88:91]
	v_mfma_f32_16x16x32_bf16 v[76:79], v[150:153], v[206:209], v[76:79]
	v_mfma_f32_16x16x32_bf16 v[72:75], v[158:161], v[206:209], v[72:75]
	v_mfma_f32_16x16x32_bf16 v[124:127], v[154:157], v[186:189], v[124:127]
	v_mfma_f32_16x16x32_bf16 v[120:123], v[162:165], v[186:189], v[120:123]
	v_mfma_f32_16x16x32_bf16 v[108:111], v[154:157], v[194:197], v[108:111]
	v_mfma_f32_16x16x32_bf16 v[104:107], v[162:165], v[194:197], v[104:107]
	v_mfma_f32_16x16x32_bf16 v[92:95], v[154:157], v[202:205], v[92:95]
	v_mfma_f32_16x16x32_bf16 v[88:91], v[162:165], v[202:205], v[88:91]
	v_mfma_f32_16x16x32_bf16 v[76:79], v[154:157], v[210:213], v[76:79]
	v_mfma_f32_16x16x32_bf16 v[72:75], v[162:165], v[210:213], v[72:75]
	s_setprio 0
	s_setprio 1
	v_mfma_f32_16x16x32_bf16 v[116:119], v[166:169], v[182:185], v[116:119]
	v_mfma_f32_16x16x32_bf16 v[112:115], v[174:177], v[182:185], v[112:115]
	v_mfma_f32_16x16x32_bf16 v[100:103], v[166:169], v[190:193], v[100:103]
	v_mfma_f32_16x16x32_bf16 v[96:99], v[174:177], v[190:193], v[96:99]
	v_mfma_f32_16x16x32_bf16 v[84:87], v[166:169], v[198:201], v[84:87]
	v_mfma_f32_16x16x32_bf16 v[80:83], v[174:177], v[198:201], v[80:83]
	v_mfma_f32_16x16x32_bf16 v[68:71], v[166:169], v[206:209], v[68:71]
	v_mfma_f32_16x16x32_bf16 v[64:67], v[174:177], v[206:209], v[64:67]
	v_mfma_f32_16x16x32_bf16 v[116:119], v[170:173], v[186:189], v[116:119]
	v_mfma_f32_16x16x32_bf16 v[112:115], v[178:181], v[186:189], v[112:115]
	v_mfma_f32_16x16x32_bf16 v[100:103], v[170:173], v[194:197], v[100:103]
	v_mfma_f32_16x16x32_bf16 v[96:99], v[178:181], v[194:197], v[96:99]
	v_mfma_f32_16x16x32_bf16 v[84:87], v[170:173], v[202:205], v[84:87]
	v_mfma_f32_16x16x32_bf16 v[80:83], v[178:181], v[202:205], v[80:83]
	v_mfma_f32_16x16x32_bf16 v[68:71], v[170:173], v[210:213], v[68:71]
	v_mfma_f32_16x16x32_bf16 v[64:67], v[178:181], v[210:213], v[64:67]
	s_setprio 0
	s_barrier
	s_add_i32 s12, s33, s20
	v_lshl_add_u64 v[142:143], s[16:17], 0, v[132:133]
	s_mov_b32 m0, s12
	ds_read_b128 v[182:185], v147 offset:16384
	ds_read_b128 v[186:189], v147 offset:17408
	ds_read_b128 v[190:193], v147 offset:18432
	ds_read_b128 v[194:197], v147 offset:19456
	ds_read_b128 v[198:201], v147 offset:20480
	ds_read_b128 v[202:205], v147 offset:21504
	ds_read_b128 v[206:209], v147 offset:22528
	ds_read_b128 v[210:213], v147 offset:23552
	global_load_lds_dwordx4 v[142:143], off
	s_add_i32 m0, s12, 0x2000
	s_add_u32 s12, s16, 0xb0000
	v_lshl_add_u64 v[214:215], s[16:17], 0, v[128:129]
	s_addc_u32 s13, s17, 0
	s_add_i32 s61, s34, s20
	global_load_lds_dwordx4 v[214:215], off
	v_lshl_add_u64 v[216:217], s[12:13], 0, v[132:133]
	s_mov_b32 m0, s61
	v_lshl_add_u64 v[218:219], s[18:19], 0, v[130:131]
	global_load_lds_dwordx4 v[216:217], off
	v_lshl_add_u64 v[216:217], s[12:13], 0, v[128:129]
	s_add_i32 m0, s61, 0x2000
	s_nop 0
	global_load_lds_dwordx4 v[216:217], off
	v_lshl_add_u64 v[216:217], s[18:19], 0, v[134:135]
	s_mov_b32 m0, s22
	s_nop 0
	global_load_lds_dwordx4 v[216:217], off
	s_mov_b32 m0, s23
	s_nop 0
	global_load_lds_dwordx4 v[218:219], off
	s_waitcnt vmcnt(8)
	s_waitcnt lgkmcnt(0)
	s_barrier
; #define PG8_STAGE(bufoff, gbase, voff) do { _Pragma("unroll") for (int _i = 0; _i < 2; ++_i) \
;     __builtin_amdgcn_global_load_lds((const unsigned*)((const char*)(gbase) + (voff)[_i]), (PG8_LAS unsigned*)(lds + (bufoff) + ldsw + _i * 8192), 16, 0, 0); } while (0)
; #define PG8_LDA(dst, b, h) do { _Pragma("unroll") for (int m = 0; m < 4; ++m) _Pragma("unroll") for (int k = 0; k < 2; ++k) dst[m][k] = *(const PG8_LAS bf16x8*)(lds + PG8_SA(b, h) + aoff + m * 2048 + k * 1024); } while (0)
; #define PG8_LDB(dst, b, h) do { _Pragma("unroll") for (int n = 0; n < 2; ++n) _Pragma("unroll") for (int k = 0; k < 2; ++k) dst[n][k] = *(const PG8_LAS bf16x8*)(lds + PG8_SB(b, h) + boff + n * 2048 + k * 1024); } while (0)
; #define PG8_MMA(ai, bj, At, Bt) do { __builtin_amdgcn_s_setprio(1); _Pragma("unroll") for (int m = 0; m < 4; ++m) _Pragma("unroll") for (int n = 0; n < 2; ++n) _Pragma("unroll") for (int k = 0; k < 2; ++k) \
;     acc[ai][bj][m][n] = __builtin_amdgcn_mfma_f32_16x16x32_bf16(Bt[n][k], At[m][k], acc[ai][bj][m][n], 0, 0, 0); __builtin_amdgcn_s_setprio(0); } while (0)
; #define PG8_WAIT_V(n) asm volatile("s_waitcnt vmcnt(" #n ")" ::: "memory")
; #define PG8_WAIT_L(n) asm volatile("s_waitcnt lgkmcnt(" #n ")" ::: "memory")
; #define PG8_BAR __builtin_amdgcn_s_barrier()
; #define PG8_SCHED __builtin_amdgcn_sched_barrier(0)
; template <class Epi, class Sched>
; DI void gemm_phase(PG8_LAS unsigned char* lds, const Gemm g, const Sched& S, const Epi& E) {
;     ...
;       PG8_WAIT_V(8); PG8_WAIT_L(0); PG8_BAR; PG8_MMA(1, 0, At, B0); PG8_MMA(1, 1, At, B1); PG8_BAR; PG8_SCHED;
;       PG8_LDB(B0, 1, 0); PG8_LDB(B1, 1, 1); PG8_SCHED; PG8_LDA(At, 1, 0); PG8_STAGE(PG8_SA(0, 1), a2 + hstepA, voffA);
;       PG8_WAIT_V(8); PG8_WAIT_L(0); PG8_BAR; PG8_MMA(0, 0, At, B0); PG8_MMA(0, 1, At, B1); PG8_BAR; PG8_SCHED;
	s_setprio 1
	s_waitcnt lgkmcnt(0)
	v_mfma_f32_16x16x32_bf16 v[60:63], v[150:153], v[182:185], v[60:63]
	v_mfma_f32_16x16x32_bf16 v[56:59], v[158:161], v[182:185], v[56:59]
	v_mfma_f32_16x16x32_bf16 v[44:47], v[150:153], v[190:193], v[44:47]
	v_mfma_f32_16x16x32_bf16 v[40:43], v[158:161], v[190:193], v[40:43]
	v_mfma_f32_16x16x32_bf16 v[28:31], v[150:153], v[198:201], v[28:31]
	v_mfma_f32_16x16x32_bf16 v[24:27], v[158:161], v[198:201], v[24:27]
	v_mfma_f32_16x16x32_bf16 v[16:19], v[150:153], v[206:209], v[16:19]
	v_mfma_f32_16x16x32_bf16 v[8:11], v[158:161], v[206:209], v[8:11]
	v_mfma_f32_16x16x32_bf16 v[60:63], v[154:157], v[186:189], v[60:63]
	v_mfma_f32_16x16x32_bf16 v[56:59], v[162:165], v[186:189], v[56:59]
	v_mfma_f32_16x16x32_bf16 v[44:47], v[154:157], v[194:197], v[44:47]
	v_mfma_f32_16x16x32_bf16 v[40:43], v[162:165], v[194:197], v[40:43]
	v_mfma_f32_16x16x32_bf16 v[28:31], v[154:157], v[202:205], v[28:31]
	v_mfma_f32_16x16x32_bf16 v[24:27], v[162:165], v[202:205], v[24:27]
	v_mfma_f32_16x16x32_bf16 v[16:19], v[154:157], v[210:213], v[16:19]
	v_mfma_f32_16x16x32_bf16 v[8:11], v[162:165], v[210:213], v[8:11]
	s_setprio 0
	s_setprio 1
	v_mfma_f32_16x16x32_bf16 v[52:55], v[166:169], v[182:185], v[52:55]
	v_mfma_f32_16x16x32_bf16 v[48:51], v[174:177], v[182:185], v[48:51]
	v_mfma_f32_16x16x32_bf16 v[36:39], v[166:169], v[190:193], v[36:39]
	v_mfma_f32_16x16x32_bf16 v[32:35], v[174:177], v[190:193], v[32:35]
	v_mfma_f32_16x16x32_bf16 v[20:23], v[166:169], v[198:201], v[20:23]
	v_mfma_f32_16x16x32_bf16 v[12:15], v[174:177], v[198:201], v[12:15]
	v_mfma_f32_16x16x32_bf16 v[4:7], v[166:169], v[206:209], v[4:7]
	v_mfma_f32_16x16x32_bf16 v[0:3], v[174:177], v[206:209], v[0:3]
	v_mfma_f32_16x16x32_bf16 v[52:55], v[170:173], v[186:189], v[52:55]
	v_mfma_f32_16x16x32_bf16 v[48:51], v[178:181], v[186:189], v[48:51]
	v_mfma_f32_16x16x32_bf16 v[36:39], v[170:173], v[194:197], v[36:39]
	v_mfma_f32_16x16x32_bf16 v[32:35], v[178:181], v[194:197], v[32:35]
	v_mfma_f32_16x16x32_bf16 v[20:23], v[170:173], v[202:205], v[20:23]
	v_mfma_f32_16x16x32_bf16 v[12:15], v[178:181], v[202:205], v[12:15]
	v_mfma_f32_16x16x32_bf16 v[4:7], v[170:173], v[210:213], v[4:7]
	v_mfma_f32_16x16x32_bf16 v[0:3], v[178:181], v[210:213], v[0:3]
	s_setprio 0
	s_barrier
	s_add_i32 s61, s30, 0x110
	v_add_u32_e32 v149, s61, v144
	ds_read_b128 v[150:153], v149
	ds_read_b128 v[154:157], v149 offset:1024
	ds_read_b128 v[158:161], v149 offset:2048
	ds_read_b128 v[162:165], v149 offset:3072
	ds_read_b128 v[166:169], v148
	ds_read_b128 v[170:173], v148 offset:1024
	ds_read_b128 v[174:177], v148 offset:2048
	ds_read_b128 v[178:181], v148 offset:3072
	s_add_u32 s12, s18, 0xb0000
	s_addc_u32 s13, s19, 0
	s_mov_b32 m0, s24
	v_lshl_add_u64 v[220:221], s[12:13], 0, v[134:135]
	ds_read_b128 v[182:185], v147 offset:32768
	ds_read_b128 v[186:189], v147 offset:33792
	ds_read_b128 v[190:193], v147 offset:34816
	ds_read_b128 v[194:197], v147 offset:35840
	ds_read_b128 v[198:201], v147 offset:36864
	ds_read_b128 v[202:205], v147 offset:37888
	ds_read_b128 v[206:209], v147 offset:38912
	ds_read_b128 v[210:213], v147 offset:39936
	global_load_lds_dwordx4 v[220:221], off
	v_lshl_add_u64 v[220:221], s[12:13], 0, v[130:131]
	s_mov_b32 m0, s25
	s_nop 0
	global_load_lds_dwordx4 v[220:221], off
	s_waitcnt vmcnt(8)
	s_waitcnt lgkmcnt(0)
	s_barrier
	s_setprio 1
	s_waitcnt lgkmcnt(0)
	v_mfma_f32_16x16x32_bf16 v[124:127], v[150:153], v[182:185], v[124:127]
	v_mfma_f32_16x16x32_bf16 v[120:123], v[158:161], v[182:185], v[120:123]
	v_mfma_f32_16x16x32_bf16 v[108:111], v[150:153], v[190:193], v[108:111]
	v_mfma_f32_16x16x32_bf16 v[104:107], v[158:161], v[190:193], v[104:107]
	v_mfma_f32_16x16x32_bf16 v[92:95], v[150:153], v[198:201], v[92:95]
	v_mfma_f32_16x16x32_bf16 v[88:91], v[158:161], v[198:201], v[88:91]
	v_mfma_f32_16x16x32_bf16 v[76:79], v[150:153], v[206:209], v[76:79]
	v_mfma_f32_16x16x32_bf16 v[72:75], v[158:161], v[206:209], v[72:75]
	v_mfma_f32_16x16x32_bf16 v[124:127], v[154:157], v[186:189], v[124:127]
	v_mfma_f32_16x16x32_bf16 v[120:123], v[162:165], v[186:189], v[120:123]
	v_mfma_f32_16x16x32_bf16 v[108:111], v[154:157], v[194:197], v[108:111]
	v_mfma_f32_16x16x32_bf16 v[104:107], v[162:165], v[194:197], v[104:107]
	v_mfma_f32_16x16x32_bf16 v[92:95], v[154:157], v[202:205], v[92:95]
	v_mfma_f32_16x16x32_bf16 v[88:91], v[162:165], v[202:205], v[88:91]
	v_mfma_f32_16x16x32_bf16 v[76:79], v[154:157], v[210:213], v[76:79]
	v_mfma_f32_16x16x32_bf16 v[72:75], v[162:165], v[210:213], v[72:75]
	s_setprio 0
	s_setprio 1
	v_mfma_f32_16x16x32_bf16 v[116:119], v[166:169], v[182:185], v[116:119]
	v_mfma_f32_16x16x32_bf16 v[112:115], v[174:177], v[182:185], v[112:115]
	v_mfma_f32_16x16x32_bf16 v[100:103], v[166:169], v[190:193], v[100:103]
	v_mfma_f32_16x16x32_bf16 v[96:99], v[174:177], v[190:193], v[96:99]
	v_mfma_f32_16x16x32_bf16 v[84:87], v[166:169], v[198:201], v[84:87]
	v_mfma_f32_16x16x32_bf16 v[80:83], v[174:177], v[198:201], v[80:83]
	v_mfma_f32_16x16x32_bf16 v[68:71], v[166:169], v[206:209], v[68:71]
	v_mfma_f32_16x16x32_bf16 v[64:67], v[174:177], v[206:209], v[64:67]
	v_mfma_f32_16x16x32_bf16 v[116:119], v[170:173], v[186:189], v[116:119]
	v_mfma_f32_16x16x32_bf16 v[112:115], v[178:181], v[186:189], v[112:115]
	v_mfma_f32_16x16x32_bf16 v[100:103], v[170:173], v[194:197], v[100:103]
	v_mfma_f32_16x16x32_bf16 v[96:99], v[178:181], v[194:197], v[96:99]
	v_mfma_f32_16x16x32_bf16 v[84:87], v[170:173], v[202:205], v[84:87]
	v_mfma_f32_16x16x32_bf16 v[80:83], v[178:181], v[202:205], v[80:83]
	v_mfma_f32_16x16x32_bf16 v[68:71], v[170:173], v[210:213], v[68:71]
	v_mfma_f32_16x16x32_bf16 v[64:67], v[178:181], v[210:213], v[64:67]
	s_setprio 0
	s_barrier
; #define PG8_STAGE(bufoff, gbase, voff) do { _Pragma("unroll") for (int _i = 0; _i < 2; ++_i) \
;     __builtin_amdgcn_global_load_lds((const unsigned*)((const char*)(gbase) + (voff)[_i]), (PG8_LAS unsigned*)(lds + (bufoff) + ldsw + _i * 8192), 16, 0, 0); } while (0)
; #define PG8_LDA(dst, b, h) do { _Pragma("unroll") for (int m = 0; m < 4; ++m) _Pragma("unroll") for (int k = 0; k < 2; ++k) dst[m][k] = *(const PG8_LAS bf16x8*)(lds + PG8_SA(b, h) + aoff + m * 2048 + k * 1024); } while (0)
; #define PG8_MMA(ai, bj, At, Bt) do { __builtin_amdgcn_s_setprio(1); _Pragma("unroll") for (int m = 0; m < 4; ++m) _Pragma("unroll") for (int n = 0; n < 2; ++n) _Pragma("unroll") for (int k = 0; k < 2; ++k) \
;     acc[ai][bj][m][n] = __builtin_amdgcn_mfma_f32_16x16x32_bf16(Bt[n][k], At[m][k], acc[ai][bj][m][n], 0, 0, 0); __builtin_amdgcn_s_setprio(0); } while (0)
; #define PG8_WAIT_V(n) asm volatile("s_waitcnt vmcnt(" #n ")" ::: "memory")
; #define PG8_WAIT_L(n) asm volatile("s_waitcnt lgkmcnt(" #n ")" ::: "memory")
; #define PG8_BAR __builtin_amdgcn_s_barrier()
; #define PG8_SCHED __builtin_amdgcn_sched_barrier(0)
;   DI void operator()(const f32x4 (&acc)[2][2][4][2], const Unit& u, int wr, int wc, int fr, int fq) const {
;     const int row0 = u.pm * BM + wr * 64 + fr;
;     const size_t base = (size_t)row0 * DM + u.pn * BM + wc * 32 + 8 * fq;
;     f32x4 xv[2][4];
;     u32x4 xh[2][2];
;     ...
;     RES_LD(0)
; #pragma unroll
;     for (int i = 0; i < 8; ++i) {
;       const int ai = i >> 2, m = i & 3;
;       if (i + 1 < 8) RES_LD(i + 1)
; template <class Epi, class Sched>
; DI void gemm_phase(PG8_LAS unsigned char* lds, const Gemm g, const Sched& S, const Epi& E) {
;     ...
;       PG8_LDA(At, 1, 1); PG8_STAGE(PG8_SB(1, 0), b3, voffB); PG8_STAGE(PG8_SB(1, 1), b3 + hstepB, voffB); PG8_STAGE(PG8_SA(1, 0), a3, voffA);
;       PG8_WAIT_V(8); PG8_WAIT_L(0); PG8_BAR; PG8_MMA(1, 0, At, B0); PG8_MMA(1, 1, At, B1); PG8_BAR; PG8_SCHED;
;     }
;     if (wr == 0) PG8_BAR;
	s_add_i32 s12, s61, s20
	v_lshl_add_u64 v[142:143], v[142:143], 0, s[4:5]
	s_mov_b32 m0, s12
	ds_read_b128 v[182:185], v147 offset:49152
	ds_read_b128 v[186:189], v147 offset:50176
	ds_read_b128 v[190:193], v147 offset:51200
	ds_read_b128 v[194:197], v147 offset:52224
	ds_read_b128 v[198:201], v147 offset:53248
	ds_read_b128 v[202:205], v147 offset:54272
	ds_read_b128 v[206:209], v147 offset:55296
	ds_read_b128 v[210:213], v147 offset:56320
	global_load_lds_dwordx4 v[142:143], off
	s_add_i32 m0, s12, 0x2000
	s_add_u32 s12, s16, 0xb0080
	v_lshl_add_u64 v[142:143], v[214:215], 0, s[4:5]
	s_addc_u32 s13, s17, 0
	s_add_i32 s16, s53, s20
	global_load_lds_dwordx4 v[142:143], off
	v_lshl_add_u64 v[142:143], s[12:13], 0, v[132:133]
	s_mov_b32 m0, s16
	s_nop 0
	global_load_lds_dwordx4 v[142:143], off
	v_lshl_add_u64 v[142:143], s[12:13], 0, v[128:129]
	s_add_i32 m0, s16, 0x2000
	s_nop 0
	global_load_lds_dwordx4 v[142:143], off
	v_lshl_add_u64 v[142:143], v[216:217], 0, s[4:5]
	s_mov_b32 m0, s28
	s_nop 0
	global_load_lds_dwordx4 v[142:143], off
	v_lshl_add_u64 v[142:143], v[218:219], 0, s[4:5]
	s_mov_b32 m0, s29
	s_nop 0
	global_load_lds_dwordx4 v[142:143], off
	s_waitcnt vmcnt(8)
	s_waitcnt lgkmcnt(0)
	s_barrier
	s_setprio 1
	s_waitcnt lgkmcnt(0)
	v_mfma_f32_16x16x32_bf16 v[60:63], v[150:153], v[182:185], v[60:63]
	v_mfma_f32_16x16x32_bf16 v[56:59], v[158:161], v[182:185], v[56:59]
	v_mfma_f32_16x16x32_bf16 v[44:47], v[150:153], v[190:193], v[44:47]
	v_mfma_f32_16x16x32_bf16 v[40:43], v[158:161], v[190:193], v[40:43]
	v_mfma_f32_16x16x32_bf16 v[28:31], v[150:153], v[198:201], v[28:31]
	v_mfma_f32_16x16x32_bf16 v[24:27], v[158:161], v[198:201], v[24:27]
	v_mfma_f32_16x16x32_bf16 v[16:19], v[150:153], v[206:209], v[16:19]
	v_mfma_f32_16x16x32_bf16 v[8:11], v[158:161], v[206:209], v[8:11]
	v_mfma_f32_16x16x32_bf16 v[60:63], v[154:157], v[186:189], v[60:63]
	v_mfma_f32_16x16x32_bf16 v[56:59], v[162:165], v[186:189], v[56:59]
	v_mfma_f32_16x16x32_bf16 v[44:47], v[154:157], v[194:197], v[44:47]
	v_mfma_f32_16x16x32_bf16 v[40:43], v[162:165], v[194:197], v[40:43]
	v_mfma_f32_16x16x32_bf16 v[28:31], v[154:157], v[202:205], v[28:31]
	v_mfma_f32_16x16x32_bf16 v[24:27], v[162:165], v[202:205], v[24:27]
	v_mfma_f32_16x16x32_bf16 v[16:19], v[154:157], v[210:213], v[16:19]
	v_mfma_f32_16x16x32_bf16 v[8:11], v[162:165], v[210:213], v[8:11]
	s_setprio 0
	s_setprio 1
	v_mfma_f32_16x16x32_bf16 v[52:55], v[166:169], v[182:185], v[52:55]
	v_mfma_f32_16x16x32_bf16 v[48:51], v[174:177], v[182:185], v[48:51]
	v_mfma_f32_16x16x32_bf16 v[36:39], v[166:169], v[190:193], v[36:39]
	v_mfma_f32_16x16x32_bf16 v[32:35], v[174:177], v[190:193], v[32:35]
	v_mfma_f32_16x16x32_bf16 v[20:23], v[166:169], v[198:201], v[20:23]
	v_mfma_f32_16x16x32_bf16 v[12:15], v[174:177], v[198:201], v[12:15]
	v_mfma_f32_16x16x32_bf16 v[4:7], v[166:169], v[206:209], v[4:7]
	v_mfma_f32_16x16x32_bf16 v[0:3], v[174:177], v[206:209], v[0:3]
	v_mfma_f32_16x16x32_bf16 v[52:55], v[170:173], v[186:189], v[52:55]
	v_mfma_f32_16x16x32_bf16 v[48:51], v[178:181], v[186:189], v[48:51]
	v_mfma_f32_16x16x32_bf16 v[36:39], v[170:173], v[194:197], v[36:39]
	v_mfma_f32_16x16x32_bf16 v[32:35], v[178:181], v[194:197], v[32:35]
	v_mfma_f32_16x16x32_bf16 v[20:23], v[170:173], v[202:205], v[20:23]
	v_mfma_f32_16x16x32_bf16 v[12:15], v[178:181], v[202:205], v[12:15]
	v_mfma_f32_16x16x32_bf16 v[4:7], v[170:173], v[210:213], v[4:7]
	v_mfma_f32_16x16x32_bf16 v[0:3], v[178:181], v[210:213], v[0:3]
	s_setprio 0
	s_barrier
	s_add_i32 s60, s60, 2
	s_add_u32 s58, s58, 0x100
	s_addc_u32 s59, s59, 0
	s_cmp_gt_u32 s60, 41
	s_mov_b64 s[12:13], s[14:15]
	s_cbranch_scc0 .LBB0_1456
	v_lshl_add_u32 v142, s57, 8, v137
	v_ashrrev_i32_e32 v143, 31, v142
	s_lshl_b32 s12, s56, 8
	v_lshlrev_b64 v[142:143], 10, v[142:143]
	s_ashr_i32 s13, s12, 31
	v_lshl_add_u64 v[166:167], v[142:143], 0, s[12:13]
	v_or_b32_e32 v166, v166, v136
	v_lshl_add_u64 v[142:143], v[166:167], 1, s[50:51]
	v_add_co_u32_e32 v162, vcc, s31, v142
	global_load_dwordx4 v[150:153], v[142:143], off
	global_load_dwordx4 v[154:157], v[142:143], off offset:256
	v_addc_co_u32_e32 v163, vcc, 0, v143, vcc
	global_load_dwordx4 v[158:161], v[162:163], off
	s_nop 0
	global_load_dwordx4 v[162:165], v[162:163], off offset:256
	s_mov_b32 s100, 0x10000
	s_mov_b32 s101, 0
	v_lshl_add_u64 v[226:227], v[142:143], 0, s[100:101]
	global_load_dwordx4 v[228:231], v[226:227], off
	global_load_dwordx4 v[228:231], v[226:227], off offset:256
	s_mov_b32 s100, 0x18000
	s_mov_b32 s101, 0
	v_lshl_add_u64 v[226:227], v[142:143], 0, s[100:101]
	global_load_dwordx4 v[228:231], v[226:227], off
	global_load_dwordx4 v[228:231], v[226:227], off offset:256
	s_mov_b32 s100, 0x40000
	s_mov_b32 s101, 0
	v_lshl_add_u64 v[226:227], v[142:143], 0, s[100:101]
	global_load_dwordx4 v[228:231], v[226:227], off
	global_load_dwordx4 v[228:231], v[226:227], off offset:256
	s_mov_b32 s100, 0x48000
	s_mov_b32 s101, 0
	v_lshl_add_u64 v[226:227], v[142:143], 0, s[100:101]
	global_load_dwordx4 v[228:231], v[226:227], off
	global_load_dwordx4 v[228:231], v[226:227], off offset:256
	s_mov_b32 s100, 0x50000
	s_mov_b32 s101, 0
	v_lshl_add_u64 v[226:227], v[142:143], 0, s[100:101]
	global_load_dwordx4 v[228:231], v[226:227], off
	global_load_dwordx4 v[228:231], v[226:227], off offset:256
	s_mov_b32 s100, 0x58000
	s_mov_b32 s101, 0
	v_lshl_add_u64 v[226:227], v[142:143], 0, s[100:101]
	global_load_dwordx4 v[228:231], v[226:227], off
	global_load_dwordx4 v[228:231], v[226:227], off offset:256
	s_and_b64 vcc, exec, s[6:7]
	s_cbranch_vccz .LBB0_1459
	s_barrier
